# hybrid norm forget-logit weight table in LDS: padded layout (lane stride 272 B) removes 16-way bank conflicts on 32 ds_read_b128 per iteration
# speedup vs baseline: 1.0081x; 1.0081x over previous
.LBB0_28:
	s_or_b64 exec, exec, s[2:3]
	s_load_dwordx2 s[36:37], s[0:1], 0x120
	s_lshr_b32 s33, s23, 6
	v_mbcnt_lo_u32_b32 v254, -1, 0
	s_waitcnt lgkmcnt(0)
	s_barrier
	s_cmp_lt_i32 s36, 1
	s_cselect_b64 s[2:3], -1, 0
	s_cmp_gt_i32 s37, 0
	s_cselect_b64 s[4:5], -1, 0
	s_and_b64 s[2:3], s[2:3], s[4:5]
	s_andn2_b64 vcc, exec, s[2:3]
	s_cbranch_vccnz .LBB0_107
	s_and_b32 s2, s23, 0xffffffc0
	s_add_u32 s12, s0, 0x130
	v_mbcnt_hi_u32_b32 v205, -1, v254
	s_addc_u32 s13, s1, 0
	s_add_i32 s3, 0, 0x20030
	v_mov_b32_e32 v16, v205
	v_mov_b32_e32 v0, s3
	ds_read_b64 v[2:3], v0
	s_load_dword s17, s[0:1], 0x130
	v_add_u32_e32 v0, s2, v16
	s_movk_i32 s2, 0x400
	v_cmp_gt_i32_e32 vcc, s2, v0
	s_waitcnt lgkmcnt(0)
	v_readfirstlane_b32 s4, v2
	v_readfirstlane_b32 s5, v3
	s_and_saveexec_b64 s[2:3], vcc
	s_cbranch_execz .LBB0_32
	s_movk_i32 s6, 0x2820
	v_mov_b64_e32 v[4:5], s[4:5]
	v_add_u32_e32 v2, 0xfffffe00, v0
	v_mad_i64_i32 v[0:1], s[6:7], v0, s6, v[4:5]
	s_mov_b64 s[6:7], 0x2010
	s_nop 0
	v_lshl_add_u64 v[0:1], v[0:1], 0, s[6:7]
	s_lshl_b32 s6, s33, 11
	s_add_i32 s6, s6, 0
	v_lshl_add_u32 v3, v16, 5, s6
	v_add_u32_e32 v3, 0x17010, v3
	v_lshrrev_b32_e32 v12, 3, v16
	v_lshl_add_u32 v3, v12, 4, v3
	s_lshl_b32 s6, s33, 7
	v_add_u32_e32 v3, s6, v3
	s_mov_b64 s[6:7], 0
	s_mov_b64 s[8:9], 0x504000
	s_movk_i32 s10, 0x1ff
.LBB0_31:
	v_add_co_u32_e32 v12, vcc, -16, v0
	v_add_u32_e32 v2, 0x200, v2
	s_nop 0
	v_addc_co_u32_e32 v13, vcc, -1, v1, vcc
	flat_load_dwordx4 v[4:7], v[12:13]
	flat_load_dwordx4 v[8:11], v[0:1]
	v_add_u32_e32 v12, -16, v3
	v_cmp_lt_i32_e32 vcc, s10, v2
	v_lshl_add_u64 v[0:1], v[0:1], 0, s[8:9]
	s_or_b64 s[6:7], vcc, s[6:7]
	s_waitcnt vmcnt(0) lgkmcnt(0)
	ds_write_b128 v12, v[4:7]
	ds_write_b128 v3, v[8:11]
	v_add_u32_e32 v3, 0x4400, v3
	s_andn2_b64 exec, exec, s[6:7]
	s_cbranch_execnz .LBB0_31

; #define LAS __attribute__((address_space(3)))
; #define GAS __attribute__((address_space(1)))
; template <int MODE, bool XBF>
; __device__ __forceinline__ void rmsnorm_rows(const void* x, const float* gain, bf16_t* H, int gw, int NGW, int lane, const LAS float* WF, const float* fbias, float* LF) {
;     constexpr int RB = MODE == 1 ? 4 : 8;
;     f32x4 g[2][2];
; #pragma unroll
;     for (int j = 0; j < 2; ++j) { g[j][0] = *(const GAS f32x4*)(gain + 512 * j + lane * 8); g[j][1] = *(const GAS f32x4*)(gain + 512 * j + lane * 8 + 4); }
;     for (int row0 = gw * RB; row0 < T; row0 += NGW * RB) {
;     ...
;             const bool hi32 = (lane & 32) != 0, hi16 = (lane & 16) != 0, hi8 = (lane & 8) != 0;
;             const int hsel = (hi32 ? 4 : 0) + (hi16 ? 2 : 0) + (hi8 ? 1 : 0);
;             const float fb = fbias[hsel];
.LBB0_47:
	s_add_i32 s2, 0, 0x20000
	v_mov_b32_e32 v0, s2
	ds_read_b64 v[0:1], v0
	s_add_i32 s2, 0, 0x20008
	v_mov_b32_e32 v2, s2
	s_add_i32 s2, 0, 0x20118
	s_add_i32 s4, 0, 0x20038
	s_waitcnt lgkmcnt(0)
	v_readfirstlane_b32 s14, v0
	v_readfirstlane_b32 s24, v1
	ds_read_b64 v[0:1], v2
	v_mov_b32_e32 v2, s2
	v_mov_b32_e32 v3, s4
	s_mov_b32 s15, 0
	s_cmpk_gt_i32 s16, 0x1fff
	s_waitcnt lgkmcnt(0)
	v_readfirstlane_b32 s2, v0
	v_readfirstlane_b32 s3, v1
	ds_read_b64 v[0:1], v2
	s_waitcnt lgkmcnt(0)
	v_readfirstlane_b32 s19, v0
	v_readfirstlane_b32 s20, v1
	ds_read_b64 v[0:1], v3
	s_waitcnt lgkmcnt(0)
	v_readfirstlane_b32 s8, v0
	v_readfirstlane_b32 s9, v1
	ds_read_b64 v[0:1], v2
	s_waitcnt lgkmcnt(0)
	v_readfirstlane_b32 s10, v0
	v_readfirstlane_b32 s11, v1
	s_cbranch_scc1 .LBB0_58
	v_ashrrev_i32_e32 v19, 31, v18
	v_lshlrev_b64 v[20:21], 2, v[18:19]
	v_lshl_add_u64 v[22:23], s[2:3], 0, v[20:21]
	global_load_dwordx4 v[0:3], v[22:23], off offset:16
	global_load_dwordx4 v[4:7], v[22:23], off
	global_load_dwordx4 v[8:11], v[22:23], off offset:2064
	global_load_dwordx4 v[12:15], v[22:23], off offset:2048
	v_and_b32_e32 v17, 64, v205
	v_add_u32_e32 v17, 64, v17
	v_xor_b32_e32 v22, 32, v205
	v_cmp_lt_i32_e32 vcc, v22, v17
	v_mov_b32_e32 v23, 0
	s_lshl_b32 s16, s16, 2
	v_cndmask_b32_e32 v22, v205, v22, vcc
	v_lshlrev_b32_e32 v206, 2, v22
	v_xor_b32_e32 v22, 16, v205
	v_cmp_lt_i32_e32 vcc, v22, v17
	s_lshl_b32 s18, s17, 5
	s_ashr_i32 s17, s16, 31
	v_cndmask_b32_e32 v22, v205, v22, vcc
	v_lshlrev_b32_e32 v207, 2, v22
	v_xor_b32_e32 v22, 8, v205
	v_cmp_lt_i32_e32 vcc, v22, v17
	s_movk_i32 s26, 0xc7f0
	s_movk_i32 s28, 0xcff0
	v_cndmask_b32_e32 v22, v205, v22, vcc
	v_lshlrev_b32_e32 v208, 2, v22
	v_xor_b32_e32 v22, 4, v205
	v_cmp_lt_i32_e32 vcc, v22, v17
	s_movk_i32 s30, 0xd7f0
	s_movk_i32 s34, 0xdff0
	v_cndmask_b32_e32 v22, v205, v22, vcc
	v_lshlrev_b32_e32 v209, 2, v22
	v_xor_b32_e32 v22, 2, v205
	v_cmp_lt_i32_e32 vcc, v22, v17
	s_movk_i32 s38, 0xe7f0
	s_mov_b32 s27, -1
	v_cndmask_b32_e32 v22, v205, v22, vcc
	v_lshlrev_b32_e32 v210, 2, v22
	v_xor_b32_e32 v22, 1, v205
	v_cmp_lt_i32_e32 vcc, v22, v17
	s_mov_b32 s29, -1
	s_mov_b32 s31, -1
	v_cndmask_b32_e32 v17, v205, v22, vcc
	v_lshlrev_b32_e32 v211, 2, v17
	v_and_b32_e32 v17, 32, v16
	v_cmp_eq_u32_e64 s[2:3], 0, v17
	v_and_b32_e32 v17, 16, v16
	v_cmp_eq_u32_e64 s[4:5], 0, v17
	v_and_b32_e32 v17, 8, v16
	v_cmp_eq_u32_e64 s[6:7], 0, v17
	v_bfe_u32 v17, v16, 3, 3
	v_lshlrev_b32_e32 v22, 2, v17
	v_lshl_add_u64 v[144:145], s[8:9], 0, v[22:23]
	v_and_b32_e32 v22, 7, v16
	v_cmp_eq_u32_e64 s[8:9], 0, v22
	v_lshlrev_b32_e32 v22, 14, v17
	v_lshl_add_u64 v[146:147], s[10:11], 0, v[22:23]
	s_lshl_b64 s[10:11], s[16:17], 11
	s_add_u32 s10, s19, s10
	s_addc_u32 s11, s20, s11
	v_lshlrev_b32_e32 v22, 8, v16
	v_lshl_add_u64 v[16:17], v[18:19], 1, s[10:11]
	s_mov_b64 s[10:11], 0x1701c00
	s_ashr_i32 s19, s18, 31
	v_lshl_add_u64 v[148:149], v[16:17], 0, s[10:11]
	s_lshl_b64 s[20:21], s[18:19], 11
	s_lshl_b64 s[10:11], s[16:17], 12
	s_add_u32 s10, s14, s10
	s_addc_u32 s11, s24, s11
	v_lshl_add_u64 v[16:17], s[10:11], 0, v[20:21]
	s_mov_b64 s[10:11], 0x3810
	v_lshl_add_u64 v[150:151], v[16:17], 0, s[10:11]
	v_add_u32_e32 v16, 0, v22
	s_lshl_b64 s[24:25], s[18:19], 12
	s_movk_i32 s17, 0xe000
	s_mov_b32 s35, -1
	s_mov_b32 s39, -1
	s_movk_i32 s19, 0xf000
	s_mov_b32 s40, 0x3a800000
	s_mov_b32 s42, 0x358637bd
	s_mov_b32 s41, 0x800000
	v_lshrrev_b32_e32 v212, 4, v16
	v_add_u32_e32 v212, v212, v16
	v_add_u32_e32 v212, 0x17000, v212
	s_mov_b32 s43, 0xbfb8aa3b
	s_mov_b32 s44, 0x3f2aaaab
	v_mov_b32_e32 v213, 0x3ecc95a3
	s_mov_b32 s45, 0x3f317218
	s_mov_b32 s46, 0x7f800000
	s_mov_b32 s47, 0x33800000
	v_mov_b32_e32 v152, 0x3f317218
	v_mov_b32_e32 v214, 0x7f800000
	v_mov_b32_e32 v215, 0x7fc00000
	v_mov_b32_e32 v216, 0xff800000
	s_branch .LBB0_50

; #define GAS __attribute__((address_space(1)))
; template <int MODE, bool XBF>
; __device__ __forceinline__ void rmsnorm_rows(const void* x, const float* gain, bf16_t* H, int gw, int NGW, int lane, const LAS float* WF, const float* fbias, float* LF) {
;     ...
;         f32x4 v[RB][2][2]; float s[RB];
; #pragma unroll
;         for (int r = 0; r < RB; ++r)
; #pragma unroll
;             for (int j = 0; j < 2; ++j) { const size_t xo = (size_t)(row0 + r) * D + 512 * j + lane * 8;
;                 if (XBF) unpack8h(*(const GAS u32x4*)((const bf16_t*)x + xo), v[r][j][0], v[r][j][1]);
;                 else { v[r][j][0] = *(const GAS f32x4*)((const float*)x + xo); v[r][j][1] = *(const GAS f32x4*)((const float*)x + xo + 4); } }
; #pragma unroll
;         for (int r = 0; r < RB; ++r) { s[r] = 0.f;
; #pragma unroll
;             for (int j = 0; j < 2; ++j)
; #pragma unroll
;                 for (int e = 0; e < 2; ++e) s[r] += (v[r][j][e][0] * v[r][j][e][0] + v[r][j][e][1] * v[r][j][e][1]) + (v[r][j][e][2] * v[r][j][e][2] + v[r][j][e][3] * v[r][j][e][3]); }
; #pragma unroll
;         for (int o = 1; o < 64; o <<= 1)
; #pragma unroll
;             for (int r = 0; r < RB; ++r) s[r] += __shfl_xor(s[r], o);
.LBB0_50:
	s_waitcnt lgkmcnt(0)
	v_lshl_add_u64 v[16:17], v[150:151], 0, s[26:27]
	v_lshl_add_u64 v[20:21], v[150:151], 0, s[28:29]
	global_load_dwordx4 v[32:35], v[16:17], off offset:16
	global_load_dwordx4 v[36:39], v[20:21], off offset:16
	v_lshl_add_u64 v[16:17], v[150:151], 0, s[30:31]
	v_add_co_u32_e32 v24, vcc, 0xffffd000, v150
	global_load_dwordx4 v[16:19], v[16:17], off offset:16
	s_nop 0
	v_addc_co_u32_e32 v25, vcc, -1, v151, vcc
	v_lshl_add_u64 v[20:21], v[150:151], 0, s[34:35]
	v_add_co_u32_e32 v48, vcc, s17, v150
	global_load_dwordx4 v[20:23], v[20:21], off offset:16
	s_nop 0
	global_load_dwordx4 v[44:47], v[24:25], off offset:-2064
	global_load_dwordx4 v[40:43], v[24:25], off offset:-16
	v_addc_co_u32_e32 v49, vcc, -1, v151, vcc
	global_load_dwordx4 v[28:31], v[48:49], off offset:-2064
	global_load_dwordx4 v[24:27], v[48:49], off offset:-16
	v_add_co_u32_e32 v48, vcc, s19, v150
	v_mov_b64_e32 v[86:87], s[42:43]
	v_add_co_u32_e64 v90, s[10:11], s19, v148
	s_and_b32 s48, s16, 0xffc
	s_nop 0
	v_addc_co_u32_e64 v91, s[10:11], -1, v149, s[10:11]
	s_ashr_i32 s10, s16, 12
	s_ashr_i32 s11, s10, 31
	s_lshl_b64 s[10:11], s[10:11], 17
	s_waitcnt vmcnt(0)
	v_pk_mul_f32 v[50:51], v[34:35], v[34:35]
	v_pk_mul_f32 v[52:53], v[32:33], v[32:33]
	s_waitcnt vmcnt(6)
	v_mul_f32_e32 v67, v39, v39
	v_pk_mov_b32 v[58:59], v[52:53], v[50:51] op_sel:[1,0]
	v_mov_b32_e32 v53, v51
	s_waitcnt vmcnt(5)
	v_pk_mul_f32 v[54:55], v[18:19], v[18:19]
	v_pk_mul_f32 v[56:57], v[16:17], v[16:17]
	v_pk_add_f32 v[52:53], v[58:59], v[52:53]
	v_pk_mov_b32 v[50:51], v[56:57], v[54:55] op_sel:[1,0]
	v_mov_b32_e32 v57, v55
	v_pk_add_f32 v[50:51], v[50:51], v[56:57]
	s_waitcnt vmcnt(3)
	v_pk_mul_f32 v[54:55], v[46:47], v[46:47]
	v_pk_mul_f32 v[60:61], v[44:45], v[44:45]
	s_waitcnt vmcnt(2)
	v_mul_f32_e32 v64, v43, v43
	v_pk_mov_b32 v[56:57], v[60:61], v[54:55] op_sel:[1,0]
	v_mov_b32_e32 v61, v55
	s_waitcnt vmcnt(1)
	v_pk_mul_f32 v[54:55], v[30:31], v[30:31]
	v_pk_mul_f32 v[58:59], v[28:29], v[28:29]
	v_pk_add_f32 v[56:57], v[56:57], v[60:61]
	v_pk_mov_b32 v[60:61], v[58:59], v[54:55] op_sel:[1,0]
	v_mov_b32_e32 v59, v55
	v_mul_f32_e32 v69, v22, v22
	v_mul_f32_e32 v62, v41, v41
	v_pk_fma_f32 v[64:65], v[42:43], v[42:43], v[64:65] op_sel_hi:[1,1,0]
	s_waitcnt vmcnt(0)
	v_mul_f32_e32 v66, v25, v25
	v_mul_f32_e32 v68, v27, v27
	v_pk_add_f32 v[58:59], v[60:61], v[58:59]
	v_mul_f32_e32 v49, v38, v38
	v_mul_f32_e32 v70, v23, v23
	v_mul_f32_e32 v71, v36, v36
	v_mul_f32_e32 v72, v37, v37
	v_mul_f32_e32 v73, v20, v20
	v_mul_f32_e32 v74, v21, v21
	v_pk_fma_f32 v[62:63], v[40:41], v[40:41], v[62:63] op_sel_hi:[1,1,0]
	v_pk_add_f32 v[52:53], v[52:53], v[52:53] op_sel:[0,1] op_sel_hi:[1,0]
	v_pk_add_f32 v[50:51], v[50:51], v[50:51] op_sel:[0,1] op_sel_hi:[1,0]
	v_mov_b32_e32 v65, v67
	v_pk_fma_f32 v[54:55], v[24:25], v[24:25], v[66:67] op_sel_hi:[1,1,0]
	v_pk_fma_f32 v[66:67], v[26:27], v[26:27], v[68:69] op_sel_hi:[1,1,0]
	v_pk_add_f32 v[56:57], v[56:57], v[56:57] op_sel:[0,1] op_sel_hi:[1,0]
	v_pk_add_f32 v[58:59], v[58:59], v[58:59] op_sel:[0,1] op_sel_hi:[1,0]
	v_mov_b32_e32 v63, v49
	v_mov_b32_e32 v53, v72
	v_mov_b32_e32 v51, v74
	v_mov_b32_e32 v55, v69
	v_mov_b32_e32 v67, v70
	v_mov_b32_e32 v57, v71
	v_mov_b32_e32 v59, v73
	v_pk_add_f32 v[62:63], v[62:63], v[64:65]
	v_pk_add_f32 v[54:55], v[54:55], v[66:67]
	v_pk_add_f32 v[52:53], v[56:57], v[52:53]
	v_pk_add_f32 v[50:51], v[58:59], v[50:51]
	v_pk_add_f32 v[52:53], v[52:53], v[62:63]
	v_pk_add_f32 v[50:51], v[50:51], v[54:55]
	v_mov_b32_e32 v55, v52
	v_mov_b32_e32 v54, v50
	v_mov_b32_e32 v52, v51
	v_pk_add_f32 v[50:51], v[54:55], v[52:53]
	ds_bpermute_b32 v53, v211, v51
	ds_bpermute_b32 v52, v211, v50
	v_addc_co_u32_e32 v49, vcc, -1, v151, vcc
	global_load_dwordx4 v[72:75], v[48:49], off offset:-2064
	v_lshl_add_u64 v[54:55], v[150:151], 0, s[38:39]
	s_waitcnt lgkmcnt(0)
	v_pk_add_f32 v[50:51], v[50:51], v[52:53]
	ds_bpermute_b32 v53, v210, v51
	ds_bpermute_b32 v52, v210, v50
	global_load_dwordx4 v[76:79], v[54:55], off offset:16
	global_load_dwordx4 v[64:67], v[150:151], off offset:-4096
	global_load_dwordx4 v[68:71], v[48:49], off offset:-16
	global_load_dwordx4 v[60:63], v[150:151], off offset:-2064
	global_load_dwordx4 v[56:59], v[150:151], off offset:-2048
	s_waitcnt lgkmcnt(0)
	v_pk_add_f32 v[50:51], v[50:51], v[52:53]
	ds_bpermute_b32 v53, v209, v51
	ds_bpermute_b32 v52, v209, v50
	s_waitcnt lgkmcnt(0)
	v_pk_add_f32 v[48:49], v[50:51], v[52:53]
	ds_bpermute_b32 v51, v208, v49
	ds_bpermute_b32 v50, v208, v48
	s_waitcnt lgkmcnt(0)
	v_pk_add_f32 v[48:49], v[48:49], v[50:51]
	ds_bpermute_b32 v51, v207, v49
	ds_bpermute_b32 v50, v207, v48
	s_waitcnt lgkmcnt(0)
	v_pk_add_f32 v[80:81], v[48:49], v[50:51]
	global_load_dwordx4 v[48:51], v[150:151], off
	global_load_dwordx4 v[52:55], v[150:151], off offset:-16
	ds_bpermute_b32 v83, v206, v81
	ds_bpermute_b32 v82, v206, v80
	ds_read_b128 v[96:99], v212 offset:17472
	ds_read_b128 v[104:107], v212 offset:17504
	ds_read_b128 v[108:111], v212 offset:17520
	ds_read_b128 v[112:115], v212 offset:17536
	s_waitcnt lgkmcnt(4)
; #define LAS __attribute__((address_space(3)))
; #define GAS __attribute__((address_space(1)))
; template <int MODE, bool XBF>
; __device__ __forceinline__ void rmsnorm_rows(const void* x, const float* gain, bf16_t* H, int gw, int NGW, int lane, const LAS float* WF, const float* fbias, float* LF) {
;     ...
;         for (int r = 0; r < RB; ++r) {
;             const int row = row0 + r;
;             const float rstd = rsqrtf(s[r] * (1.f / D) + 1e-6f);
;             const size_t hrow = MODE == 2 ? (size_t)row + (row >> 12) + 1 : (size_t)row;
; #pragma unroll
;             for (int j = 0; j < 2; ++j) { v[r][j][0] = v[r][j][0] * rstd * g[j][0]; v[r][j][1] = v[r][j][1] * rstd * g[j][1];
;                 *(GAS u32x4*)(H + hrow * D + 512 * j + lane * 8) = pack8(v[r][j][0], v[r][j][1]); }
;     ...
;             for (int j = 0; j < 2; ++j)
; #pragma unroll
;                 for (int e = 0; e < 2; ++e)
; #pragma unroll
;                     for (int c = 0; c < 4; ++c) {
;                         const LAS float* wp = WF + (512 * j + lane * 8 + 4 * e + c) * 8;
;                         const f32x4 w0 = *(const LAS f32x4*)wp, w1 = *(const LAS f32x4*)(wp + 4);
	v_pk_add_f32 v[80:81], v[80:81], v[82:83]
	ds_read_b128 v[120:123], v212 offset:17568
	ds_read_b128 v[140:143], v212 offset:17584
	v_pk_fma_f32 v[88:89], v[80:81], s[40:41], v[86:87] op_sel_hi:[1,0,0]
	ds_read_b128 v[136:139], v212 offset:17600
	ds_read_b128 v[132:135], v212 offset:17616
	v_mul_f32_e32 v80, 0x4b800000, v89
	v_cmp_gt_f32_e32 vcc, s41, v89
	ds_read_b128 v[128:131], v212 offset:17632
	s_nop 0
	v_cndmask_b32_e32 v80, v89, v80, vcc
	v_rsq_f32_e32 v80, v80
	s_nop 0
	v_mul_f32_e32 v81, 0x45800000, v80
	v_cndmask_b32_e32 v80, v80, v81, vcc
	v_pk_mul_f32 v[44:45], v[44:45], v[80:81] op_sel_hi:[1,0]
	v_pk_mul_f32 v[46:47], v[46:47], v[80:81] op_sel_hi:[1,0]
	v_pk_mul_f32 v[92:93], v[32:33], v[80:81] op_sel_hi:[1,0]
	v_pk_mul_f32 v[34:35], v[34:35], v[80:81] op_sel_hi:[1,0]
	v_pk_mul_f32 v[40:41], v[40:41], v[80:81] op_sel_hi:[1,0]
	v_pk_mul_f32 v[42:43], v[42:43], v[80:81] op_sel_hi:[1,0]
	v_pk_mul_f32 v[94:95], v[36:37], v[80:81] op_sel_hi:[1,0]
	v_pk_mul_f32 v[38:39], v[38:39], v[80:81] op_sel_hi:[1,0]
	v_pk_mul_f32 v[82:83], v[6:7], v[46:47]
	v_pk_mul_f32 v[32:33], v[4:5], v[44:45]
	v_pk_mul_f32 v[84:85], v[2:3], v[34:35]
	v_pk_mul_f32 v[80:81], v[0:1], v[92:93]
	v_cvt_pk_bf16_f32 v34, v32, v33
	v_cvt_pk_bf16_f32 v35, v82, v83
	v_cvt_pk_bf16_f32 v36, v80, v81
	v_cvt_pk_bf16_f32 v37, v84, v85
	global_store_dwordx4 v[90:91], v[34:37], off offset:-3072
	v_cmp_gt_f32_e32 vcc, s41, v88
	v_pk_mul_f32 v[116:117], v[14:15], v[42:43]
	v_mul_f32_e32 v36, 0x4b800000, v88
	v_pk_mul_f32 v[100:101], v[12:13], v[40:41]
	v_pk_mul_f32 v[170:171], v[10:11], v[38:39]
	v_pk_mul_f32 v[124:125], v[8:9], v[94:95]
	v_cndmask_b32_e32 v36, v88, v36, vcc
	v_cvt_pk_bf16_f32 v34, v100, v101
	v_cvt_pk_bf16_f32 v35, v116, v117
	v_rsq_f32_e32 v44, v36
	v_cvt_pk_bf16_f32 v36, v124, v125
	v_cvt_pk_bf16_f32 v37, v170, v171
	global_store_dwordx4 v[90:91], v[34:37], off offset:-2048
	v_mul_f32_e32 v45, 0x45800000, v44
	ds_read_b128 v[92:95], v212 offset:17456
	s_waitcnt vmcnt(9)
	v_pk_mul_f32 v[34:35], v[74:75], v[74:75]
	v_pk_mul_f32 v[36:37], v[72:73], v[72:73]
	s_nop 0
	v_pk_mov_b32 v[38:39], v[36:37], v[34:35] op_sel:[1,0]
	v_mov_b32_e32 v37, v35
	v_pk_add_f32 v[34:35], v[38:39], v[36:37]
	s_waitcnt vmcnt(8)
	v_pk_mul_f32 v[36:37], v[78:79], v[78:79]
	v_pk_mul_f32 v[38:39], v[76:77], v[76:77]
	v_pk_add_f32 v[34:35], v[34:35], v[34:35] op_sel:[0,1] op_sel_hi:[1,0]
	v_pk_mov_b32 v[40:41], v[38:39], v[36:37] op_sel:[1,0]
	v_mov_b32_e32 v39, v37
	v_pk_add_f32 v[36:37], v[40:41], v[38:39]
	s_waitcnt vmcnt(7)
	v_mul_f32_e32 v35, v64, v64
	v_pk_add_f32 v[36:37], v[36:37], v[36:37] op_sel:[0,1] op_sel_hi:[1,0]
	s_waitcnt vmcnt(6)
	v_mul_f32_e32 v38, v71, v71
	v_mul_f32_e32 v37, v65, v65
	v_pk_add_f32 v[34:35], v[34:35], v[36:37]
	v_mul_f32_e32 v36, v69, v69
	v_pk_fma_f32 v[36:37], v[68:69], v[68:69], v[36:37] op_sel_hi:[1,1,0]
	v_pk_fma_f32 v[38:39], v[70:71], v[70:71], v[38:39] op_sel_hi:[1,1,0]
	v_mul_f32_e32 v37, v66, v66
	v_mul_f32_e32 v39, v67, v67
	v_pk_add_f32 v[36:37], v[36:37], v[38:39]
	s_waitcnt vmcnt(5)
	v_pk_mul_f32 v[38:39], v[60:61], v[60:61]
	v_pk_add_f32 v[34:35], v[34:35], v[36:37]
	v_pk_mul_f32 v[36:37], v[62:63], v[62:63]
	s_nop 0
	v_pk_mov_b32 v[40:41], v[38:39], v[36:37] op_sel:[1,0]
	v_mov_b32_e32 v39, v37
	v_pk_add_f32 v[36:37], v[40:41], v[38:39]
	s_waitcnt vmcnt(4)
	v_pk_mul_f32 v[38:39], v[58:59], v[58:59]
	v_pk_mul_f32 v[40:41], v[56:57], v[56:57]
	v_pk_add_f32 v[36:37], v[36:37], v[36:37] op_sel:[0,1] op_sel_hi:[1,0]
	v_pk_mov_b32 v[42:43], v[40:41], v[38:39] op_sel:[1,0]
	v_mov_b32_e32 v41, v39
	v_pk_add_f32 v[38:39], v[42:43], v[40:41]
	s_waitcnt vmcnt(3)
	v_mul_f32_e32 v37, v48, v48
	v_pk_add_f32 v[38:39], v[38:39], v[38:39] op_sel:[0,1] op_sel_hi:[1,0]
	s_waitcnt vmcnt(2)
	v_mul_f32_e32 v40, v55, v55
	v_mul_f32_e32 v39, v49, v49
	v_pk_add_f32 v[36:37], v[36:37], v[38:39]
	v_mul_f32_e32 v38, v53, v53
	v_pk_fma_f32 v[38:39], v[52:53], v[52:53], v[38:39] op_sel_hi:[1,1,0]
	v_pk_fma_f32 v[40:41], v[54:55], v[54:55], v[40:41] op_sel_hi:[1,1,0]
	v_mul_f32_e32 v39, v50, v50
	v_mul_f32_e32 v41, v51, v51
	v_pk_add_f32 v[38:39], v[38:39], v[40:41]
	ds_read_b128 v[40:43], v212 offset:112
	v_pk_add_f32 v[36:37], v[36:37], v[38:39]
	v_mov_b32_e32 v39, v34
	v_mov_b32_e32 v38, v36
	v_mov_b32_e32 v34, v37
	v_pk_add_f32 v[34:35], v[38:39], v[34:35]
	ds_bpermute_b32 v37, v211, v35
	ds_bpermute_b32 v36, v211, v34
	v_cndmask_b32_e32 v38, v44, v45, vcc
	v_pk_mul_f32 v[28:29], v[28:29], v[38:39] op_sel_hi:[1,0]
	v_pk_mul_f32 v[30:31], v[30:31], v[38:39] op_sel_hi:[1,0]
	v_pk_mul_f32 v[202:203], v[4:5], v[28:29]
	s_waitcnt lgkmcnt(0)
	v_pk_add_f32 v[34:35], v[34:35], v[36:37]
	ds_bpermute_b32 v37, v210, v35
	ds_bpermute_b32 v36, v210, v34
	v_pk_mul_f32 v[200:201], v[6:7], v[30:31]
	v_pk_mul_f32 v[16:17], v[16:17], v[38:39] op_sel_hi:[1,0]
	v_pk_mul_f32 v[18:19], v[18:19], v[38:39] op_sel_hi:[1,0]
	v_pk_mul_f32 v[198:199], v[0:1], v[16:17]
	s_waitcnt lgkmcnt(0)
	v_pk_add_f32 v[28:29], v[34:35], v[36:37]
	ds_bpermute_b32 v31, v209, v29
	ds_bpermute_b32 v30, v209, v28
	v_pk_mul_f32 v[196:197], v[2:3], v[18:19]
	v_cvt_pk_bf16_f32 v16, v202, v203
	v_cvt_pk_bf16_f32 v17, v200, v201
	v_cvt_pk_bf16_f32 v18, v198, v199
	s_waitcnt lgkmcnt(0)
	v_pk_add_f32 v[28:29], v[28:29], v[30:31]
	ds_bpermute_b32 v31, v208, v29
	ds_bpermute_b32 v30, v208, v28
	v_cvt_pk_bf16_f32 v19, v196, v197
	global_store_dwordx4 v[90:91], v[16:19], off offset:-1024
	v_pk_mul_f32 v[20:21], v[20:21], v[38:39] op_sel_hi:[1,0]
	v_pk_mul_f32 v[22:23], v[22:23], v[38:39] op_sel_hi:[1,0]
	v_pk_mul_f32 v[16:17], v[24:25], v[38:39] op_sel_hi:[1,0]
	s_waitcnt lgkmcnt(0)
; #define LAS __attribute__((address_space(3)))
; #define GAS __attribute__((address_space(1)))
; template <int MODE, bool XBF>
; __device__ __forceinline__ void rmsnorm_rows(const void* x, const float* gain, bf16_t* H, int gw, int NGW, int lane, const LAS float* WF, const float* fbias, float* LF) {
;     ...
;         for (int r = 0; r < RB; ++r) {
;             const int row = row0 + r;
;             const float rstd = rsqrtf(s[r] * (1.f / D) + 1e-6f);
;             const size_t hrow = MODE == 2 ? (size_t)row + (row >> 12) + 1 : (size_t)row;
; #pragma unroll
;             for (int j = 0; j < 2; ++j) { v[r][j][0] = v[r][j][0] * rstd * g[j][0]; v[r][j][1] = v[r][j][1] * rstd * g[j][1];
;                 *(GAS u32x4*)(H + hrow * D + 512 * j + lane * 8) = pack8(v[r][j][0], v[r][j][1]); }
;         }
;         if (MODE == 1) {
;             float dt[RB][8];
; #pragma unroll
;             for (int r = 0; r < RB; ++r)
; #pragma unroll
;                 for (int h = 0; h < 8; ++h) dt[r][h] = 0.f;
; #pragma unroll
;             for (int j = 0; j < 2; ++j)
; #pragma unroll
;                 for (int e = 0; e < 2; ++e)
; #pragma unroll
;                     for (int c = 0; c < 4; ++c) {
;                         const LAS float* wp = WF + (512 * j + lane * 8 + 4 * e + c) * 8;
;                         const f32x4 w0 = *(const LAS f32x4*)wp, w1 = *(const LAS f32x4*)(wp + 4);
; #pragma unroll
;                         for (int r = 0; r < RB; ++r) {
;                             const float hv = v[r][j][e][c];
;                             dt[r][0] += hv * w0[0]; dt[r][1] += hv * w0[1]; dt[r][2] += hv * w0[2]; dt[r][3] += hv * w0[3];
;                             dt[r][4] += hv * w1[0]; dt[r][5] += hv * w1[1]; dt[r][6] += hv * w1[2]; dt[r][7] += hv * w1[3];
;                         }
	v_pk_add_f32 v[24:25], v[28:29], v[30:31]
	v_pk_mul_f32 v[18:19], v[26:27], v[38:39] op_sel_hi:[1,0]
	ds_bpermute_b32 v27, v207, v25
	ds_bpermute_b32 v26, v207, v24
	v_pk_mul_f32 v[192:193], v[14:15], v[18:19]
	v_pk_mul_f32 v[190:191], v[8:9], v[20:21]
	v_pk_mul_f32 v[194:195], v[12:13], v[16:17]
	v_pk_mul_f32 v[188:189], v[10:11], v[22:23]
	s_waitcnt lgkmcnt(0)
	v_pk_add_f32 v[18:19], v[24:25], v[26:27]
	ds_bpermute_b32 v25, v206, v19
	ds_bpermute_b32 v24, v206, v18
	v_cvt_pk_bf16_f32 v16, v194, v195
	v_cvt_pk_bf16_f32 v17, v192, v193
	ds_read_b128 v[28:31], v212 offset:16
	ds_read_b128 v[36:39], v212 offset:64
	s_waitcnt lgkmcnt(2)
	v_pk_add_f32 v[18:19], v[18:19], v[24:25]
	ds_read_b128 v[44:47], v212 offset:96
	v_pk_fma_f32 v[20:21], v[18:19], s[40:41], v[86:87] op_sel_hi:[1,0,0]
	v_cvt_pk_bf16_f32 v19, v188, v189
	v_mul_f32_e32 v18, 0x4b800000, v21
	v_cmp_gt_f32_e32 vcc, s41, v21
	s_waitcnt lgkmcnt(2)
	v_fma_f32 v220, v28, v32, 0
	v_fma_f32 v221, v29, v32, 0
	v_cndmask_b32_e32 v18, v21, v18, vcc
	v_rsq_f32_e32 v21, v18
	v_cvt_pk_bf16_f32 v18, v190, v191
	global_store_dwordx4 v[148:149], v[16:19], off offset:-4096
	v_fma_f32 v222, v30, v32, 0
	v_fma_f32 v223, v31, v32, 0
	v_mul_f32_e32 v16, 0x45800000, v21
	v_cndmask_b32_e32 v22, v21, v16, vcc
	v_pk_mul_f32 v[16:17], v[72:73], v[22:23] op_sel_hi:[1,0]
	v_pk_mul_f32 v[18:19], v[74:75], v[22:23] op_sel_hi:[1,0]
	v_pk_mul_f32 v[24:25], v[76:77], v[22:23] op_sel_hi:[1,0]
	v_pk_mul_f32 v[26:27], v[78:79], v[22:23] op_sel_hi:[1,0]
	v_pk_mul_f32 v[184:185], v[6:7], v[18:19]
	v_pk_mul_f32 v[186:187], v[4:5], v[16:17]
	v_pk_mul_f32 v[180:181], v[2:3], v[26:27]
	v_pk_mul_f32 v[182:183], v[0:1], v[24:25]
	v_cvt_pk_bf16_f32 v16, v186, v187
	v_cvt_pk_bf16_f32 v17, v184, v185
	v_cvt_pk_bf16_f32 v18, v182, v183
	v_cvt_pk_bf16_f32 v19, v180, v181
	global_store_dwordx4 v[148:149], v[16:19], off offset:-3072
	v_cmp_gt_f32_e32 vcc, s41, v20
	v_pk_mul_f32 v[24:25], v[64:65], v[22:23] op_sel_hi:[1,0]
	v_pk_mul_f32 v[18:19], v[70:71], v[22:23] op_sel_hi:[1,0]
	v_pk_mul_f32 v[16:17], v[68:69], v[22:23] op_sel_hi:[1,0]
	v_pk_mul_f32 v[176:177], v[14:15], v[18:19]
	v_mul_f32_e32 v18, 0x4b800000, v20
	v_cndmask_b32_e32 v18, v20, v18, vcc
	v_rsq_f32_e32 v20, v18
	v_pk_mul_f32 v[22:23], v[66:67], v[22:23] op_sel_hi:[1,0]
	v_pk_mul_f32 v[178:179], v[12:13], v[16:17]
	v_pk_mul_f32 v[172:173], v[10:11], v[22:23]
	v_pk_mul_f32 v[174:175], v[8:9], v[24:25]
	v_cvt_pk_bf16_f32 v16, v178, v179
	v_cvt_pk_bf16_f32 v17, v176, v177
	v_cvt_pk_bf16_f32 v18, v174, v175
	v_cvt_pk_bf16_f32 v19, v172, v173
	global_store_dwordx4 v[148:149], v[16:19], off offset:-2048
	ds_read_b128 v[68:71], v212 offset:192
	ds_read_b128 v[64:67], v212 offset:208
	v_mul_f32_e32 v16, 0x45800000, v20
	v_cndmask_b32_e32 v20, v20, v16, vcc
	v_pk_mul_f32 v[16:17], v[60:61], v[20:21] op_sel_hi:[1,0]
	v_pk_mul_f32 v[18:19], v[62:63], v[20:21] op_sel_hi:[1,0]
	v_pk_mul_f32 v[22:23], v[56:57], v[20:21] op_sel_hi:[1,0]
	v_pk_mul_f32 v[24:25], v[58:59], v[20:21] op_sel_hi:[1,0]
	v_pk_mul_f32 v[166:167], v[6:7], v[18:19]
	v_pk_mul_f32 v[168:169], v[4:5], v[16:17]
	v_pk_mul_f32 v[162:163], v[2:3], v[24:25]
	v_pk_mul_f32 v[164:165], v[0:1], v[22:23]
	v_cvt_pk_bf16_f32 v16, v168, v169
	v_cvt_pk_bf16_f32 v17, v166, v167
	v_cvt_pk_bf16_f32 v18, v164, v165
	v_cvt_pk_bf16_f32 v19, v162, v163
	global_store_dwordx4 v[148:149], v[16:19], off offset:-1024
	v_pk_mul_f32 v[22:23], v[48:49], v[20:21] op_sel_hi:[1,0]
	ds_read_b128 v[24:27], v212
	v_pk_mul_f32 v[16:17], v[52:53], v[20:21] op_sel_hi:[1,0]
	v_pk_mul_f32 v[18:19], v[54:55], v[20:21] op_sel_hi:[1,0]
	v_pk_mul_f32 v[20:21], v[50:51], v[20:21] op_sel_hi:[1,0]
	v_pk_mul_f32 v[158:159], v[14:15], v[18:19]
	v_pk_mul_f32 v[160:161], v[12:13], v[16:17]
	v_pk_mul_f32 v[154:155], v[10:11], v[20:21]
	v_pk_mul_f32 v[156:157], v[8:9], v[22:23]
	v_cvt_pk_bf16_f32 v16, v160, v161
	v_cvt_pk_bf16_f32 v17, v158, v159
	v_cvt_pk_bf16_f32 v18, v156, v157
	v_cvt_pk_bf16_f32 v19, v154, v155
	ds_read_b128 v[20:23], v212 offset:32
	global_store_dwordx4 v[148:149], v[16:19], off
	ds_read_b128 v[16:19], v212 offset:48
	s_waitcnt lgkmcnt(2)
	v_fma_f32 v153, v24, v32, 0
	v_fma_f32 v204, v25, v32, 0
	v_fma_f32 v218, v26, v32, 0
	v_fma_f32 v219, v27, v32, 0
	s_waitcnt lgkmcnt(1)
	v_fmac_f32_e32 v153, v33, v20
	v_fmac_f32_e32 v204, v33, v21
	v_fmac_f32_e32 v218, v33, v22
	v_fmac_f32_e32 v219, v33, v23
	s_waitcnt lgkmcnt(0)
	v_fmac_f32_e32 v220, v33, v16
	v_fmac_f32_e32 v221, v33, v17
	v_fmac_f32_e32 v222, v33, v18
	v_fmac_f32_e32 v223, v33, v19
	ds_read_b128 v[32:35], v212 offset:80
	flat_load_dword v217, v[144:145]
	ds_read_b128 v[52:55], v212 offset:128
	ds_read_b128 v[48:51], v212 offset:144
	ds_read_b128 v[60:63], v212 offset:160
	ds_read_b128 v[56:59], v212 offset:176
	v_fmac_f32_e32 v153, v82, v36
	v_fmac_f32_e32 v204, v82, v37
	v_fmac_f32_e32 v218, v82, v38
	v_fmac_f32_e32 v219, v82, v39
	s_waitcnt lgkmcnt(0)
	v_fmac_f32_e32 v220, v82, v32
	v_fmac_f32_e32 v221, v82, v33
	v_fmac_f32_e32 v222, v82, v34
	v_fmac_f32_e32 v223, v82, v35
	ds_read_b128 v[72:75], v212 offset:224
	ds_read_b128 v[76:79], v212 offset:240
	v_fmac_f32_e32 v153, v83, v44
	v_fmac_f32_e32 v204, v83, v45
	v_fmac_f32_e32 v218, v83, v46
	v_fmac_f32_e32 v219, v83, v47
	v_fmac_f32_e32 v220, v83, v40
	v_fmac_f32_e32 v221, v83, v41
	v_fmac_f32_e32 v222, v83, v42
	v_fmac_f32_e32 v223, v83, v43
	v_fmac_f32_e32 v153, v80, v52
	v_fmac_f32_e32 v204, v80, v53
	v_fmac_f32_e32 v218, v80, v54
	v_fmac_f32_e32 v219, v80, v55
	v_fmac_f32_e32 v220, v80, v48
	v_fmac_f32_e32 v221, v80, v49
	v_fmac_f32_e32 v222, v80, v50
	v_fmac_f32_e32 v223, v80, v51
	v_fmac_f32_e32 v153, v81, v60
	v_fmac_f32_e32 v204, v81, v61
	v_fmac_f32_e32 v218, v81, v62
	v_fmac_f32_e32 v219, v81, v63
	v_fmac_f32_e32 v220, v81, v56
	v_fmac_f32_e32 v221, v81, v57
	v_fmac_f32_e32 v222, v81, v58
	v_fmac_f32_e32 v223, v81, v59
	v_fmac_f32_e32 v153, v84, v68
	v_fmac_f32_e32 v204, v84, v69
	v_fmac_f32_e32 v218, v84, v70
	v_fmac_f32_e32 v219, v84, v71
	v_fmac_f32_e32 v220, v84, v64
	v_fmac_f32_e32 v221, v84, v65
	v_fmac_f32_e32 v222, v84, v66
	v_fmac_f32_e32 v223, v84, v67
	s_waitcnt lgkmcnt(0)
; #define LAS __attribute__((address_space(3)))
; template <int MODE, bool XBF>
; __device__ __forceinline__ void rmsnorm_rows(const void* x, const float* gain, bf16_t* H, int gw, int NGW, int lane, const LAS float* WF, const float* fbias, float* LF) {
;     ...
;             for (int j = 0; j < 2; ++j)
; #pragma unroll
;                 for (int e = 0; e < 2; ++e)
; #pragma unroll
;                     for (int c = 0; c < 4; ++c) {
;                         const LAS float* wp = WF + (512 * j + lane * 8 + 4 * e + c) * 8;
;                         const f32x4 w0 = *(const LAS f32x4*)wp, w1 = *(const LAS f32x4*)(wp + 4);
; #pragma unroll
;                         for (int r = 0; r < RB; ++r) {
;                             const float hv = v[r][j][e][c];
;                             dt[r][0] += hv * w0[0]; dt[r][1] += hv * w0[1]; dt[r][2] += hv * w0[2]; dt[r][3] += hv * w0[3];
;                             dt[r][4] += hv * w1[0]; dt[r][5] += hv * w1[1]; dt[r][6] += hv * w1[2]; dt[r][7] += hv * w1[3];
;                         }
;                     }
;             const bool hi32 = (lane & 32) != 0, hi16 = (lane & 16) != 0, hi8 = (lane & 8) != 0;
;             const int hsel = (hi32 ? 4 : 0) + (hi16 ? 2 : 0) + (hi8 ? 1 : 0);
;             const float fb = fbias[hsel];
; #pragma unroll
;             for (int r = 0; r < RB; ++r) {
;                 float d4[4], d2[2], d1;
; #pragma unroll
;                 for (int k = 0; k < 4; ++k) { const float send = hi32 ? dt[r][k] : dt[r][k + 4], keep = hi32 ? dt[r][k + 4] : dt[r][k]; d4[k] = keep + __shfl_xor(send, 32); }
; #pragma unroll
;                 for (int k = 0; k < 2; ++k) { const float send = hi16 ? d4[k] : d4[k + 2], keep = hi16 ? d4[k + 2] : d4[k]; d2[k] = keep + __shfl_xor(send, 16); }
;                 { const float send = hi8 ? d2[0] : d2[1], keep = hi8 ? d2[1] : d2[0]; d1 = keep + __shfl_xor(send, 8); }
;                 d1 += __shfl_xor(d1, 4); d1 += __shfl_xor(d1, 2); d1 += __shfl_xor(d1, 1);
	v_fmac_f32_e32 v153, v85, v72
	v_fmac_f32_e32 v204, v85, v73
	v_fmac_f32_e32 v218, v85, v74
	v_fmac_f32_e32 v219, v85, v75
	v_fmac_f32_e32 v220, v85, v76
	ds_read_b128 v[80:83], v212 offset:17408
	v_fmac_f32_e32 v221, v85, v77
	v_fmac_f32_e32 v222, v85, v78
	v_fmac_f32_e32 v223, v85, v79
	ds_read_b128 v[84:87], v212 offset:17424
	ds_read_b128 v[88:91], v212 offset:17440
	s_waitcnt lgkmcnt(0)
	v_fmac_f32_e32 v153, v100, v80
	v_fmac_f32_e32 v204, v100, v81
	v_fmac_f32_e32 v218, v100, v82
	v_fmac_f32_e32 v219, v100, v83
	v_fmac_f32_e32 v220, v100, v84
	v_fmac_f32_e32 v221, v100, v85
	v_fmac_f32_e32 v222, v100, v86
	v_fmac_f32_e32 v223, v100, v87
	v_fmac_f32_e32 v153, v101, v88
	v_fmac_f32_e32 v204, v101, v89
	v_fmac_f32_e32 v218, v101, v90
	v_fmac_f32_e32 v219, v101, v91
	v_fmac_f32_e32 v220, v101, v92
	v_fmac_f32_e32 v221, v101, v93
	v_fmac_f32_e32 v222, v101, v94
	v_fmac_f32_e32 v223, v101, v95
	ds_read_b128 v[100:103], v212 offset:17488
	v_fmac_f32_e32 v153, v116, v96
	v_fmac_f32_e32 v204, v116, v97
	v_fmac_f32_e32 v218, v116, v98
	v_fmac_f32_e32 v219, v116, v99
	s_waitcnt lgkmcnt(0)
	v_fmac_f32_e32 v220, v116, v100
	v_fmac_f32_e32 v221, v116, v101
	v_fmac_f32_e32 v222, v116, v102
	v_fmac_f32_e32 v223, v116, v103
	v_fmac_f32_e32 v153, v117, v104
	v_fmac_f32_e32 v204, v117, v105
	v_fmac_f32_e32 v218, v117, v106
	v_fmac_f32_e32 v219, v117, v107
	v_fmac_f32_e32 v220, v117, v108
	v_fmac_f32_e32 v221, v117, v109
	v_fmac_f32_e32 v222, v117, v110
	v_fmac_f32_e32 v223, v117, v111
	ds_read_b128 v[116:119], v212 offset:17552
	v_fmac_f32_e32 v153, v124, v112
	v_fmac_f32_e32 v204, v124, v113
	v_fmac_f32_e32 v218, v124, v114
	v_fmac_f32_e32 v219, v124, v115
	s_waitcnt lgkmcnt(0)
	v_fmac_f32_e32 v220, v124, v116
	v_fmac_f32_e32 v221, v124, v117
	v_fmac_f32_e32 v222, v124, v118
	v_fmac_f32_e32 v223, v124, v119
	v_fmac_f32_e32 v153, v125, v120
	v_fmac_f32_e32 v204, v125, v121
	v_fmac_f32_e32 v218, v125, v122
	v_fmac_f32_e32 v219, v125, v123
	v_fmac_f32_e32 v220, v125, v140
	v_fmac_f32_e32 v221, v125, v141
	v_fmac_f32_e32 v222, v125, v142
	v_fmac_f32_e32 v223, v125, v143
	ds_read_b128 v[124:127], v212 offset:17648
	v_fmac_f32_e32 v153, v170, v136
	v_fmac_f32_e32 v220, v170, v132
	v_fmac_f32_e32 v153, v171, v128
	v_fmac_f32_e32 v204, v170, v137
	s_waitcnt lgkmcnt(0)
	v_fmac_f32_e32 v220, v171, v124
	v_fmac_f32_e32 v218, v170, v138
	v_fmac_f32_e32 v219, v170, v139
	v_fmac_f32_e32 v221, v170, v133
	v_fmac_f32_e32 v222, v170, v134
	v_fmac_f32_e32 v223, v170, v135
	v_cndmask_b32_e64 v170, v153, v220, s[2:3]
	ds_bpermute_b32 v170, v206, v170
	v_fmac_f32_e32 v204, v171, v129
	v_fmac_f32_e32 v221, v171, v125
	v_cndmask_b32_e64 v153, v220, v153, s[2:3]
	v_fmac_f32_e32 v218, v171, v130
	v_fmac_f32_e32 v222, v171, v126
	s_waitcnt lgkmcnt(0)
	v_add_f32_e32 v153, v153, v170
	v_cndmask_b32_e64 v170, v204, v221, s[2:3]
	v_fmac_f32_e32 v219, v171, v131
	v_fmac_f32_e32 v223, v171, v127
	v_cndmask_b32_e64 v171, v221, v204, s[2:3]
	ds_bpermute_b32 v170, v206, v170
	v_cndmask_b32_e64 v204, v218, v222, s[2:3]
	ds_bpermute_b32 v204, v206, v204
	v_cndmask_b32_e64 v220, v219, v223, s[2:3]
	ds_bpermute_b32 v220, v206, v220
	s_waitcnt lgkmcnt(0)
	v_add_f32_e32 v170, v171, v170
	v_cndmask_b32_e64 v171, v222, v218, s[2:3]
	v_add_f32_e32 v171, v171, v204
	v_cndmask_b32_e64 v204, v223, v219, s[2:3]
	v_add_f32_e32 v204, v204, v220
	v_cndmask_b32_e64 v218, v153, v171, s[4:5]
	v_cndmask_b32_e64 v219, v170, v204, s[4:5]
	ds_bpermute_b32 v218, v207, v218
	ds_bpermute_b32 v219, v207, v219
	v_cndmask_b32_e64 v153, v171, v153, s[4:5]
	v_cndmask_b32_e64 v170, v204, v170, s[4:5]
	s_waitcnt lgkmcnt(0)
	v_add_f32_e32 v153, v153, v218
	v_add_f32_e32 v170, v170, v219
	v_cndmask_b32_e64 v171, v153, v170, s[6:7]
	ds_bpermute_b32 v171, v208, v171
	v_cndmask_b32_e64 v153, v170, v153, s[6:7]
	s_waitcnt lgkmcnt(0)
	v_add_f32_e32 v153, v153, v171
	ds_bpermute_b32 v170, v209, v153
	s_waitcnt lgkmcnt(0)
	v_add_f32_e32 v153, v153, v170
	ds_bpermute_b32 v170, v210, v153
	s_waitcnt lgkmcnt(0)
	v_add_f32_e32 v153, v153, v170
	ds_bpermute_b32 v218, v211, v153
	v_lshl_add_u64 v[170:171], v[146:147], 0, s[10:11]
	s_and_saveexec_b64 s[10:11], s[8:9]
	s_cbranch_execz .LBB0_52
; template <int MODE, bool XBF>
; __device__ __forceinline__ void rmsnorm_rows(const void* x, const float* gain, bf16_t* H, int gw, int NGW, int lane, const LAS float* WF, const float* fbias, float* LF) {
;     ...
;                 if ((lane & 7) == 0) {
;                     const int row = row0 + r;
;                     const float z = d1 + fb;
;                     LF[((size_t)(row >> 12) * 8 + hsel) * S + (row & 4095)] = fminf(z, 0.f) - log1pf(__expf(-fabsf(z)));
;                 }
	s_waitcnt lgkmcnt(0)
	v_add_f32_e32 v153, v153, v218
	s_waitcnt vmcnt(0)
	v_add_f32_e32 v153, v217, v153
	v_mul_f32_e64 v204, |v153|, s43
	v_exp_f32_e32 v204, v204
	v_min_f32_e32 v232, 0, v153
	s_lshl_b32 s14, s48, 2
	v_add_f32_e32 v153, 1.0, v204
	v_add_f32_e32 v218, -1.0, v153
	v_sub_f32_e32 v219, v218, v153
	v_sub_f32_e32 v218, v204, v218
	v_add_f32_e32 v219, 1.0, v219
	v_frexp_mant_f32_e32 v220, v153
	v_add_f32_e32 v221, v218, v219
	v_cvt_f64_f32_e32 v[218:219], v153
	v_frexp_exp_i32_f64_e32 v218, v[218:219]
	v_cmp_gt_f32_e32 vcc, s44, v220
	s_nop 1
	v_subbrev_co_u32_e32 v226, vcc, 0, v218, vcc
	v_sub_u32_e32 v218, 0, v226
	v_ldexp_f32 v153, v153, v218
	v_add_f32_e32 v220, -1.0, v153
	v_add_f32_e32 v219, 1.0, v220
	v_ldexp_f32 v218, v221, v218
	v_sub_f32_e32 v219, v153, v219
	v_add_f32_e32 v221, v218, v219
	v_add_f32_e32 v219, 1.0, v153
	v_add_f32_e32 v222, -1.0, v219
	v_sub_f32_e32 v153, v153, v222
	v_add_f32_e32 v153, v218, v153
	v_add_f32_e32 v227, v219, v153
	v_rcp_f32_e32 v228, v227
	v_sub_f32_e32 v218, v227, v219
	v_add_f32_e32 v219, v220, v221
	v_sub_f32_e32 v153, v153, v218
	v_mul_f32_e32 v230, v219, v228
	v_sub_f32_e32 v218, v219, v220
	v_mul_f32_e32 v220, v227, v230
	v_fma_f32 v222, v230, v227, -v220
	v_fmac_f32_e32 v222, v230, v153
	v_sub_f32_e32 v229, v221, v218
	v_add_f32_e32 v218, v220, v222
	v_sub_f32_e32 v221, v219, v218
	v_pk_add_f32 v[224:225], v[218:219], v[220:221] neg_lo:[0,1] neg_hi:[0,1]
	v_mov_b32_e32 v223, v218
	v_pk_add_f32 v[218:219], v[224:225], v[222:223] neg_lo:[0,1] neg_hi:[0,1]
	v_cmp_neq_f32_e32 vcc, s46, v204
	v_add_f32_e32 v219, v229, v219
	v_add_f32_e32 v218, v218, v219
	v_add_f32_e32 v219, v221, v218
	v_mul_f32_e32 v229, v228, v219
	v_mul_f32_e32 v220, v227, v229
	v_fma_f32 v222, v229, v227, -v220
	v_fmac_f32_e32 v222, v229, v153
	v_sub_f32_e32 v153, v221, v219
	v_add_f32_e32 v153, v218, v153
	v_add_f32_e32 v218, v220, v222
	v_sub_f32_e32 v221, v219, v218
	v_pk_add_f32 v[224:225], v[218:219], v[220:221] neg_lo:[0,1] neg_hi:[0,1]
	v_mov_b32_e32 v223, v218
	v_pk_add_f32 v[218:219], v[224:225], v[222:223] neg_lo:[0,1] neg_hi:[0,1]
	s_nop 0
	v_add_f32_e32 v153, v153, v219
	v_add_f32_e32 v153, v218, v153
	v_add_f32_e32 v219, v230, v229
	v_add_f32_e32 v153, v221, v153
	v_sub_f32_e32 v218, v219, v230
	v_mul_f32_e32 v153, v228, v153
	v_sub_f32_e32 v218, v229, v218
	v_add_f32_e32 v220, v218, v153
	v_add_f32_e32 v222, v219, v220
	v_cvt_f32_i32_e32 v218, v226
	v_mul_f32_e32 v223, v222, v222
	v_sub_f32_e32 v219, v222, v219
	v_fmamk_f32 v153, v223, 0x3e9b6dac, v213
	v_sub_f32_e32 v219, v220, v219
	v_fmaak_f32 v153, v223, v153, 0x3f2aaada
	v_ldexp_f32 v224, v219, 1
	v_mul_f32_e32 v219, v222, v223
	v_ldexp_f32 v221, v222, 1
	v_pk_mul_f32 v[222:223], v[218:219], v[152:153]
	s_nop 0
	v_fma_f32 v220, v218, s45, -v222
	v_fmac_f32_e32 v220, 0xb102e308, v218
	v_pk_add_f32 v[218:219], v[222:223], v[220:221]
	s_nop 0
	v_sub_f32_e32 v153, v219, v221
	v_sub_f32_e32 v153, v223, v153
	v_add_f32_e32 v225, v224, v153
	v_mov_b32_e32 v224, v222
	v_pk_add_f32 v[222:223], v[218:219], v[222:223] neg_lo:[0,1] neg_hi:[0,1]
	v_pk_add_f32 v[226:227], v[218:219], v[224:225]
	v_mov_b32_e32 v221, v218
	v_mov_b32_e32 v223, v227
	v_pk_add_f32 v[228:229], v[220:221], v[222:223] neg_lo:[0,1] neg_hi:[0,1]
	v_pk_add_f32 v[220:221], v[220:221], v[222:223]
	v_mov_b32_e32 v224, v225
	v_pk_add_f32 v[222:223], v[220:221], v[218:219] op_sel:[1,0] op_sel_hi:[0,1] neg_lo:[0,1] neg_hi:[0,1]
	v_pk_add_f32 v[230:231], v[226:227], v[222:223] op_sel_hi:[1,0] neg_lo:[0,1] neg_hi:[0,1]
	v_mov_b32_e32 v226, v227
	v_mov_b32_e32 v227, v221
	v_pk_mov_b32 v[222:223], v[218:219], v[222:223] op_sel:[1,0]
	v_mov_b32_e32 v225, v218
	v_pk_add_f32 v[222:223], v[226:227], v[222:223] neg_lo:[0,1] neg_hi:[0,1]
	v_mov_b32_e32 v230, v228
	v_pk_add_f32 v[218:219], v[224:225], v[222:223] neg_lo:[0,1] neg_hi:[0,1]
	v_mov_b32_e32 v229, v221
	v_pk_add_f32 v[222:223], v[230:231], v[218:219]
	s_nop 0
	v_pk_add_f32 v[224:225], v[222:223], v[222:223] op_sel:[0,1] op_sel_hi:[1,0]
	s_nop 0
	v_pk_add_f32 v[220:221], v[220:221], v[224:225] op_sel:[1,0] op_sel_hi:[0,1]
	v_mov_b32_e32 v223, v220
	v_pk_add_f32 v[226:227], v[222:223], v[228:229] neg_lo:[0,1] neg_hi:[0,1]
	v_mov_b32_e32 v219, v224
	v_sub_f32_e32 v153, v222, v226
	v_pk_add_f32 v[218:219], v[218:219], v[226:227] neg_lo:[0,1] neg_hi:[0,1]
	v_sub_f32_e32 v153, v228, v153
	v_add_f32_e32 v153, v218, v153
	v_add_f32_e32 v153, v153, v219
	v_add_f32_e32 v153, v220, v153
	v_cndmask_b32_e32 v153, v214, v153, vcc
	v_cmp_ngt_f32_e32 vcc, -1.0, v204
	v_lshl_add_u64 v[218:219], v[170:171], 0, s[14:15]
	s_nop 0
	v_cndmask_b32_e32 v153, v215, v153, vcc
	v_cmp_neq_f32_e32 vcc, -1.0, v204
	s_nop 1
	v_cndmask_b32_e32 v153, v216, v153, vcc
	v_cmp_lt_f32_e64 vcc, |v204|, s47
	s_nop 1
	v_cndmask_b32_e32 v153, v153, v204, vcc
	v_sub_f32_e32 v153, v232, v153
	flat_store_dword v[218:219], v153

.LBB0_1660:
	s_cmp_lt_i32 s36, 17
	s_cselect_b64 s[2:3], -1, 0
	s_cmp_gt_i32 s37, 16
	s_cselect_b64 s[4:5], -1, 0
	s_and_b64 s[2:3], s[2:3], s[4:5]
	s_andn2_b64 vcc, exec, s[2:3]
	s_cbranch_vccnz .LBB0_1739
	s_add_u32 s10, s0, 0x130
	v_mbcnt_hi_u32_b32 v202, -1, v254
	s_addc_u32 s11, s1, 0
	s_mov_b64 s[2:3], s[0:1]
	s_add_i32 s0, 0, 0x20030
	v_mov_b32_e32 v16, v202
	s_waitcnt vmcnt(0)
	v_mov_b32_e32 v0, s0
	ds_read_b64 v[2:3], v0
	s_load_dword s18, s[2:3], 0x130
	v_lshl_add_u32 v0, s33, 6, v16
	s_movk_i32 s0, 0x400
	v_cmp_gt_i32_e32 vcc, s0, v0
	s_waitcnt lgkmcnt(0)
	v_readfirstlane_b32 s4, v2
	v_readfirstlane_b32 s5, v3
	s_and_saveexec_b64 s[2:3], vcc
	s_cbranch_execz .LBB0_1664
	s_movk_i32 s0, 0x2820
	v_mov_b64_e32 v[4:5], s[4:5]
	v_add_u32_e32 v2, 0xfffffe00, v0
	v_mad_i64_i32 v[0:1], s[6:7], v0, s0, v[4:5]
	s_lshl_b32 s0, s33, 11
	s_add_i32 s0, s0, 0
	s_mov_b64 s[6:7], 0xa0a010
	v_lshl_add_u32 v3, v16, 5, s0
	v_lshl_add_u64 v[0:1], v[0:1], 0, s[6:7]
	v_add_u32_e32 v3, 0x17010, v3
	v_lshrrev_b32_e32 v12, 3, v16
	v_lshl_add_u32 v3, v12, 4, v3
	s_lshl_b32 s0, s33, 7
	v_add_u32_e32 v3, s0, v3
	s_mov_b64 s[6:7], 0
	s_mov_b64 s[8:9], 0x504000
	s_movk_i32 s12, 0x1ff
.LBB0_1663:
	v_add_co_u32_e32 v12, vcc, -16, v0
	v_add_u32_e32 v2, 0x200, v2
	s_nop 0
	v_addc_co_u32_e32 v13, vcc, -1, v1, vcc
	flat_load_dwordx4 v[4:7], v[12:13]
	flat_load_dwordx4 v[8:11], v[0:1]
	v_add_u32_e32 v12, -16, v3
	v_cmp_lt_i32_e32 vcc, s12, v2
	v_lshl_add_u64 v[0:1], v[0:1], 0, s[8:9]
	s_or_b64 s[6:7], vcc, s[6:7]
	s_waitcnt vmcnt(0) lgkmcnt(0)
	ds_write_b128 v12, v[4:7]
	ds_write_b128 v3, v[8:11]
	v_add_u32_e32 v3, 0x4400, v3
	s_andn2_b64 exec, exec, s[6:7]
	s_cbranch_execnz .LBB0_1663

; #define LAS __attribute__((address_space(3)))
; #define GAS __attribute__((address_space(1)))
; template <int MODE, bool XBF>
; __device__ __forceinline__ void rmsnorm_rows(const void* x, const float* gain, bf16_t* H, int gw, int NGW, int lane, const LAS float* WF, const float* fbias, float* LF) {
;     constexpr int RB = MODE == 1 ? 4 : 8;
;     f32x4 g[2][2];
; #pragma unroll
;     for (int j = 0; j < 2; ++j) { g[j][0] = *(const GAS f32x4*)(gain + 512 * j + lane * 8); g[j][1] = *(const GAS f32x4*)(gain + 512 * j + lane * 8 + 4); }
;     for (int row0 = gw * RB; row0 < T; row0 += NGW * RB) {
;     ...
;             const bool hi32 = (lane & 32) != 0, hi16 = (lane & 16) != 0, hi8 = (lane & 8) != 0;
;             const int hsel = (hi32 ? 4 : 0) + (hi16 ? 2 : 0) + (hi8 ? 1 : 0);
;             const float fb = fbias[hsel];
.LBB0_1679:
	s_add_i32 s0, 0, 0x20118
	v_mov_b32_e32 v2, s0
	ds_read_b64 v[0:1], v2
	s_add_i32 s0, 0, 0x20008
	v_mov_b32_e32 v3, s0
	s_add_i32 s0, 0, 0x20038
	s_mov_b32 s13, 0
	s_waitcnt lgkmcnt(0)
	v_readfirstlane_b32 s12, v0
	v_readfirstlane_b32 s23, v1
	ds_read_b64 v[0:1], v3
	v_mov_b32_e32 v3, s0
	v_readlane_b32 s0, v255, 0
	s_cmpk_gt_i32 s19, 0x1fff
	v_readlane_b32 s1, v255, 1
	s_waitcnt lgkmcnt(0)
	v_readfirstlane_b32 s2, v0
	v_readfirstlane_b32 s3, v1
	ds_read_b64 v[0:1], v2
	s_waitcnt lgkmcnt(0)
	v_readfirstlane_b32 s20, v0
	v_readfirstlane_b32 s21, v1
	ds_read_b64 v[0:1], v3
	s_waitcnt lgkmcnt(0)
	v_readfirstlane_b32 s8, v0
	v_readfirstlane_b32 s9, v1
	ds_read_b64 v[0:1], v2
	s_waitcnt lgkmcnt(0)
	v_readfirstlane_b32 s16, v0
	v_readfirstlane_b32 s17, v1
	s_cbranch_scc1 .LBB0_1690
	v_mov_b32_e32 v0, s2
	v_mov_b32_e32 v1, s3
	v_ashrrev_i32_e32 v19, 31, v18
	v_lshl_add_u64 v[0:1], v[18:19], 2, v[0:1]
	v_add_co_u32_e32 v22, vcc, 0x2000, v0
	s_mov_b64 s[2:3], 0x2000
	s_nop 0
	v_addc_co_u32_e32 v23, vcc, 0, v1, vcc
	v_lshl_add_u64 v[20:21], v[0:1], 0, s[2:3]
	global_load_dwordx4 v[0:3], v[22:23], off
	global_load_dwordx4 v[4:7], v[20:21], off offset:2064
	global_load_dwordx4 v[8:11], v[20:21], off offset:16
	global_load_dwordx4 v[12:15], v[20:21], off offset:2048
	v_and_b32_e32 v17, 64, v202
	v_add_u32_e32 v17, 64, v17
	v_xor_b32_e32 v20, 32, v202
	v_cmp_lt_i32_e32 vcc, v20, v17
	v_mov_b32_e32 v21, 0
	s_lshl_b32 s14, s19, 2
	v_cndmask_b32_e32 v20, v202, v20, vcc
	v_lshlrev_b32_e32 v203, 2, v20
	v_xor_b32_e32 v20, 16, v202
	v_cmp_lt_i32_e32 vcc, v20, v17
	s_ashr_i32 s15, s14, 31
	s_lshl_b64 s[24:25], s[14:15], 11
	v_cndmask_b32_e32 v20, v202, v20, vcc
	v_lshlrev_b32_e32 v205, 2, v20
	v_xor_b32_e32 v20, 8, v202
	v_cmp_lt_i32_e32 vcc, v20, v17
	v_lshlrev_b64 v[148:149], 1, v[18:19]
	s_mov_b32 s15, 0x5801000
	v_cndmask_b32_e32 v20, v202, v20, vcc
	v_lshlrev_b32_e32 v206, 2, v20
	v_xor_b32_e32 v20, 4, v202
	v_cmp_lt_i32_e32 vcc, v20, v17
	s_mov_b32 s26, 0x3a800000
	s_mov_b32 s28, 0x358637bd
	v_cndmask_b32_e32 v20, v202, v20, vcc
	v_lshlrev_b32_e32 v207, 2, v20
	v_xor_b32_e32 v20, 2, v202
	v_cmp_lt_i32_e32 vcc, v20, v17
	s_mov_b32 s27, 0x1701000
	s_mov_b32 s29, 0xbfb8aa3b
	v_cndmask_b32_e32 v20, v202, v20, vcc
	v_lshlrev_b32_e32 v208, 2, v20
	v_xor_b32_e32 v20, 1, v202
	v_cmp_lt_i32_e32 vcc, v20, v17
	s_mov_b32 s34, 0x3f2aaaab
	v_mov_b32_e32 v211, 0x3ecc95a3
	v_cndmask_b32_e32 v17, v202, v20, vcc
	v_lshlrev_b32_e32 v209, 2, v17
	v_and_b32_e32 v17, 32, v16
	v_cmp_eq_u32_e64 s[2:3], 0, v17
	v_and_b32_e32 v17, 16, v16
	v_cmp_eq_u32_e64 s[4:5], 0, v17
	v_and_b32_e32 v17, 8, v16
	v_cmp_eq_u32_e64 s[6:7], 0, v17
	v_bfe_u32 v17, v16, 3, 3
	v_lshlrev_b32_e32 v20, 2, v17
	v_lshl_add_u64 v[144:145], s[8:9], 0, v[20:21]
	v_and_b32_e32 v20, 7, v16
	v_cmp_eq_u32_e64 s[8:9], 0, v20
	v_lshlrev_b32_e32 v20, 14, v17
	v_lshl_add_u64 v[146:147], s[16:17], 0, v[20:21]
	s_lshl_b32 s16, s18, 5
	s_add_u32 s18, s20, s24
	s_addc_u32 s19, s21, s25
	s_ashr_i32 s17, s16, 31
	v_lshlrev_b32_e32 v16, 8, v16
	s_lshl_b64 s[20:21], s[16:17], 11
	s_add_u32 s24, s12, s24
	v_add_u32_e32 v16, 0, v16
	s_addc_u32 s25, s23, s25
	s_mov_b32 s17, 0x800000
	s_mov_b32 s23, 0x1700000
	v_lshrrev_b32_e32 v210, 4, v16
	v_add_u32_e32 v210, v210, v16
	v_add_u32_e32 v210, 0x17000, v210
	s_mov_b32 s35, 0x3f317218
	s_mov_b32 s38, 0x7f800000
	s_mov_b32 s39, 0x33800000
	v_mov_b32_e32 v150, 0x3f317218
	v_mov_b32_e32 v212, 0x7f800000
	v_mov_b32_e32 v213, 0x7fc00000
	v_mov_b32_e32 v214, 0xff800000
	s_branch .LBB0_1682

; #define GAS __attribute__((address_space(1)))
; template <int MODE, bool XBF>
; __device__ __forceinline__ void rmsnorm_rows(const void* x, const float* gain, bf16_t* H, int gw, int NGW, int lane, const LAS float* WF, const float* fbias, float* LF) {
;     ...
;         f32x4 v[RB][2][2]; float s[RB];
; #pragma unroll
;         for (int r = 0; r < RB; ++r)
; #pragma unroll
;             for (int j = 0; j < 2; ++j) { const size_t xo = (size_t)(row0 + r) * D + 512 * j + lane * 8;
;                 if (XBF) unpack8h(*(const GAS u32x4*)((const bf16_t*)x + xo), v[r][j][0], v[r][j][1]);
;                 else { v[r][j][0] = *(const GAS f32x4*)((const float*)x + xo); v[r][j][1] = *(const GAS f32x4*)((const float*)x + xo + 4); } }
; #pragma unroll
;         for (int r = 0; r < RB; ++r) { s[r] = 0.f;
; #pragma unroll
;             for (int j = 0; j < 2; ++j)
; #pragma unroll
;                 for (int e = 0; e < 2; ++e) s[r] += (v[r][j][e][0] * v[r][j][e][0] + v[r][j][e][1] * v[r][j][e][1]) + (v[r][j][e][2] * v[r][j][e][2] + v[r][j][e][3] * v[r][j][e][3]); }
; #pragma unroll
;         for (int o = 1; o < 64; o <<= 1)
; #pragma unroll
;             for (int r = 0; r < RB; ++r) s[r] += __shfl_xor(s[r], o);
.LBB0_1682:
	v_lshl_add_u64 v[24:25], s[24:25], 0, v[148:149]
	v_add_co_u32_e32 v26, vcc, s15, v24
	s_ashr_i32 s30, s14, 12
	s_nop 0
	v_addc_co_u32_e32 v27, vcc, 0, v25, vcc
	v_add_co_u32_e32 v24, vcc, 0x5800000, v24
	s_waitcnt lgkmcnt(0)
	global_load_dwordx4 v[16:19], v[26:27], off
	global_load_dwordx4 v[20:23], v[26:27], off offset:1024
	global_load_dwordx4 v[48:51], v[26:27], off offset:2048
	global_load_dwordx4 v[52:55], v[26:27], off offset:3072
	v_addc_co_u32_e32 v25, vcc, 0, v25, vcc
	global_load_dwordx4 v[56:59], v[24:25], off
	global_load_dwordx4 v[60:63], v[24:25], off offset:1024
	global_load_dwordx4 v[80:83], v[24:25], off offset:2048
	global_load_dwordx4 v[84:87], v[24:25], off offset:3072
	s_ashr_i32 s31, s30, 31
	s_lshl_b64 s[30:31], s[30:31], 17
	s_and_b32 s40, s14, 0xffc
	s_waitcnt vmcnt(0)
	v_cvt_f32_f16_e32 v42, v16
	v_cvt_f32_f16_sdwa v43, v16 dst_sel:DWORD dst_unused:UNUSED_PAD src0_sel:WORD_1
	v_cvt_f32_f16_e32 v46, v17
	s_waitcnt vmcnt(3)
	v_cvt_f32_f16_e32 v66, v56
	v_cvt_f32_f16_sdwa v67, v56 dst_sel:DWORD dst_unused:UNUSED_PAD src0_sel:WORD_1
	v_cvt_f32_f16_e32 v78, v57
	v_cvt_f32_f16_sdwa v79, v57 dst_sel:DWORD dst_unused:UNUSED_PAD src0_sel:WORD_1
	v_cvt_f32_f16_e32 v64, v58
	v_cvt_f32_f16_sdwa v65, v58 dst_sel:DWORD dst_unused:UNUSED_PAD src0_sel:WORD_1
	v_cvt_f32_f16_e32 v76, v59
	v_cvt_f32_f16_sdwa v77, v59 dst_sel:DWORD dst_unused:UNUSED_PAD src0_sel:WORD_1
	v_cvt_f32_f16_sdwa v47, v17 dst_sel:DWORD dst_unused:UNUSED_PAD src0_sel:WORD_1
	v_cvt_f32_f16_e32 v40, v18
	v_cvt_f32_f16_sdwa v41, v18 dst_sel:DWORD dst_unused:UNUSED_PAD src0_sel:WORD_1
	v_cvt_f32_f16_e32 v44, v19
	v_cvt_f32_f16_sdwa v45, v19 dst_sel:DWORD dst_unused:UNUSED_PAD src0_sel:WORD_1
	v_cvt_f32_f16_e32 v36, v20
	v_cvt_f32_f16_sdwa v37, v20 dst_sel:DWORD dst_unused:UNUSED_PAD src0_sel:WORD_1
	v_cvt_f32_f16_e32 v38, v21
	v_cvt_f32_f16_sdwa v39, v21 dst_sel:DWORD dst_unused:UNUSED_PAD src0_sel:WORD_1
	v_cvt_f32_f16_sdwa v33, v23 dst_sel:DWORD dst_unused:UNUSED_PAD src0_sel:WORD_1
	v_cvt_f32_f16_e32 v32, v23
	v_cvt_f32_f16_sdwa v35, v22 dst_sel:DWORD dst_unused:UNUSED_PAD src0_sel:WORD_1
	v_cvt_f32_f16_e32 v34, v22
	v_cvt_f32_f16_e32 v26, v48
	v_cvt_f32_f16_sdwa v27, v48 dst_sel:DWORD dst_unused:UNUSED_PAD src0_sel:WORD_1
	v_cvt_f32_f16_e32 v30, v49
	v_cvt_f32_f16_sdwa v31, v49 dst_sel:DWORD dst_unused:UNUSED_PAD src0_sel:WORD_1
	v_cvt_f32_f16_e32 v24, v50
	v_cvt_f32_f16_sdwa v25, v50 dst_sel:DWORD dst_unused:UNUSED_PAD src0_sel:WORD_1
	v_cvt_f32_f16_e32 v28, v51
	v_cvt_f32_f16_sdwa v29, v51 dst_sel:DWORD dst_unused:UNUSED_PAD src0_sel:WORD_1
	v_cvt_f32_f16_e32 v20, v52
	v_cvt_f32_f16_sdwa v21, v52 dst_sel:DWORD dst_unused:UNUSED_PAD src0_sel:WORD_1
	v_cvt_f32_f16_e32 v22, v53
	v_cvt_f32_f16_sdwa v23, v53 dst_sel:DWORD dst_unused:UNUSED_PAD src0_sel:WORD_1
	v_cvt_f32_f16_sdwa v17, v55 dst_sel:DWORD dst_unused:UNUSED_PAD src0_sel:WORD_1
	v_cvt_f32_f16_e32 v16, v55
	v_cvt_f32_f16_sdwa v19, v54 dst_sel:DWORD dst_unused:UNUSED_PAD src0_sel:WORD_1
	v_cvt_f32_f16_e32 v18, v54
	s_waitcnt vmcnt(2)
	v_cvt_f32_f16_e32 v72, v60
	v_cvt_f32_f16_sdwa v73, v60 dst_sel:DWORD dst_unused:UNUSED_PAD src0_sel:WORD_1
	v_cvt_f32_f16_e32 v74, v61
	v_cvt_f32_f16_sdwa v75, v61 dst_sel:DWORD dst_unused:UNUSED_PAD src0_sel:WORD_1
	v_cvt_f32_f16_sdwa v69, v63 dst_sel:DWORD dst_unused:UNUSED_PAD src0_sel:WORD_1
	v_cvt_f32_f16_e32 v68, v63
	v_cvt_f32_f16_sdwa v71, v62 dst_sel:DWORD dst_unused:UNUSED_PAD src0_sel:WORD_1
	v_cvt_f32_f16_e32 v70, v62
	s_waitcnt vmcnt(1)
	v_cvt_f32_f16_e32 v60, v80
	v_cvt_f32_f16_sdwa v61, v80 dst_sel:DWORD dst_unused:UNUSED_PAD src0_sel:WORD_1
	v_cvt_f32_f16_e32 v62, v81
	v_cvt_f32_f16_sdwa v63, v81 dst_sel:DWORD dst_unused:UNUSED_PAD src0_sel:WORD_1
	v_cvt_f32_f16_e32 v56, v82
	v_cvt_f32_f16_sdwa v57, v82 dst_sel:DWORD dst_unused:UNUSED_PAD src0_sel:WORD_1
	v_cvt_f32_f16_e32 v58, v83
	v_cvt_f32_f16_sdwa v59, v83 dst_sel:DWORD dst_unused:UNUSED_PAD src0_sel:WORD_1
	s_waitcnt vmcnt(0)
	v_cvt_f32_f16_e32 v52, v84
	v_cvt_f32_f16_sdwa v53, v84 dst_sel:DWORD dst_unused:UNUSED_PAD src0_sel:WORD_1
	v_cvt_f32_f16_e32 v54, v85
	v_cvt_f32_f16_sdwa v55, v85 dst_sel:DWORD dst_unused:UNUSED_PAD src0_sel:WORD_1
	v_cvt_f32_f16_sdwa v49, v87 dst_sel:DWORD dst_unused:UNUSED_PAD src0_sel:WORD_1
	v_cvt_f32_f16_e32 v48, v87
	v_cvt_f32_f16_sdwa v51, v86 dst_sel:DWORD dst_unused:UNUSED_PAD src0_sel:WORD_1
	v_cvt_f32_f16_e32 v50, v86
	v_pk_mul_f32 v[80:81], v[78:79], v[78:79]
	v_pk_mul_f32 v[82:83], v[66:67], v[66:67]
	v_pk_mul_f32 v[84:85], v[76:77], v[76:77]
	v_pk_mul_f32 v[86:87], v[64:65], v[64:65]
	v_pk_mov_b32 v[88:89], v[82:83], v[80:81] op_sel:[1,0]
	v_mov_b32_e32 v83, v81
	v_pk_mov_b32 v[80:81], v[86:87], v[84:85] op_sel:[1,0]
	v_mov_b32_e32 v87, v85
	v_pk_add_f32 v[80:81], v[80:81], v[86:87]
	v_pk_add_f32 v[82:83], v[88:89], v[82:83]
	v_pk_add_f32 v[80:81], v[80:81], v[80:81] op_sel_hi:[0,1]
	v_mul_f32_e32 v80, v72, v72
	v_pk_fma_f32 v[84:85], v[72:73], v[72:73], v[80:81] op_sel_hi:[1,1,0]
	v_mul_f32_e32 v80, v74, v74
	v_pk_add_f32 v[82:83], v[82:83], v[82:83] op_sel_hi:[0,1]
	v_pk_fma_f32 v[86:87], v[74:75], v[74:75], v[80:81] op_sel_hi:[1,1,0]
	v_mul_f32_e32 v82, v70, v70
	v_mul_f32_e32 v80, v71, v71
	v_mul_f32_e32 v84, v68, v68
	v_mul_f32_e32 v86, v69, v69
	v_pk_add_f32 v[80:81], v[82:83], v[80:81]
	v_pk_add_f32 v[82:83], v[84:85], v[86:87]
	v_pk_mul_f32 v[84:85], v[60:61], v[60:61]
	v_pk_add_f32 v[80:81], v[80:81], v[82:83]
	v_pk_mul_f32 v[82:83], v[62:63], v[62:63]
	v_mov_b32_e32 v93, v80
	v_pk_mov_b32 v[86:87], v[84:85], v[82:83] op_sel:[1,0]
	v_mov_b32_e32 v85, v83
	v_pk_add_f32 v[82:83], v[86:87], v[84:85]
	v_pk_mul_f32 v[84:85], v[58:59], v[58:59]
	v_pk_add_f32 v[82:83], v[82:83], v[82:83] op_sel_hi:[0,1]
	v_pk_mul_f32 v[86:87], v[56:57], v[56:57]
	v_mul_f32_e32 v82, v52, v52
	v_pk_mov_b32 v[88:89], v[86:87], v[84:85] op_sel:[1,0]
	v_mov_b32_e32 v87, v85
	v_pk_add_f32 v[84:85], v[88:89], v[86:87]
	v_pk_fma_f32 v[86:87], v[52:53], v[52:53], v[82:83] op_sel_hi:[1,1,0]
	v_mul_f32_e32 v82, v54, v54
	v_pk_add_f32 v[84:85], v[84:85], v[84:85] op_sel_hi:[0,1]
	v_pk_fma_f32 v[88:89], v[54:55], v[54:55], v[82:83] op_sel_hi:[1,1,0]
	v_mul_f32_e32 v82, v50, v50
	v_mul_f32_e32 v84, v51, v51
	v_mul_f32_e32 v86, v48, v48
	v_mul_f32_e32 v88, v49, v49
	v_pk_add_f32 v[82:83], v[82:83], v[84:85]
	v_pk_add_f32 v[84:85], v[86:87], v[88:89]
	v_pk_mul_f32 v[86:87], v[42:43], v[42:43]
	v_pk_add_f32 v[82:83], v[82:83], v[84:85]
	v_pk_mul_f32 v[84:85], v[46:47], v[46:47]
	v_mov_b32_e32 v92, v82
	v_mov_b32_e32 v80, v83
	v_pk_add_f32 v[80:81], v[92:93], v[80:81]
	ds_bpermute_b32 v83, v209, v81
	ds_bpermute_b32 v82, v209, v80
	v_pk_mov_b32 v[88:89], v[86:87], v[84:85] op_sel:[1,0]
	v_mov_b32_e32 v87, v85
	v_pk_add_f32 v[84:85], v[88:89], v[86:87]
	v_pk_mul_f32 v[86:87], v[44:45], v[44:45]
	s_waitcnt lgkmcnt(0)
; #define GAS __attribute__((address_space(1)))
; template <int MODE, bool XBF>
; __device__ __forceinline__ void rmsnorm_rows(const void* x, const float* gain, bf16_t* H, int gw, int NGW, int lane, const LAS float* WF, const float* fbias, float* LF) {
;     ...
; #pragma unroll
;         for (int o = 1; o < 64; o <<= 1)
; #pragma unroll
;             for (int r = 0; r < RB; ++r) s[r] += __shfl_xor(s[r], o);
; #pragma unroll
;         for (int r = 0; r < RB; ++r) {
;             const int row = row0 + r;
;             const float rstd = rsqrtf(s[r] * (1.f / D) + 1e-6f);
;             const size_t hrow = MODE == 2 ? (size_t)row + (row >> 12) + 1 : (size_t)row;
; #pragma unroll
;             for (int j = 0; j < 2; ++j) { v[r][j][0] = v[r][j][0] * rstd * g[j][0]; v[r][j][1] = v[r][j][1] * rstd * g[j][1];
;                 *(GAS u32x4*)(H + hrow * D + 512 * j + lane * 8) = pack8(v[r][j][0], v[r][j][1]); }
	v_pk_add_f32 v[80:81], v[80:81], v[82:83]
	ds_bpermute_b32 v83, v208, v81
	ds_bpermute_b32 v82, v208, v80
	v_pk_add_f32 v[84:85], v[84:85], v[84:85] op_sel_hi:[0,1]
	v_pk_mul_f32 v[88:89], v[40:41], v[40:41]
	v_mul_f32_e32 v84, v36, v36
	v_pk_mov_b32 v[90:91], v[88:89], v[86:87] op_sel:[1,0]
	s_waitcnt lgkmcnt(0)
	v_pk_add_f32 v[80:81], v[80:81], v[82:83]
	ds_bpermute_b32 v83, v207, v81
	ds_bpermute_b32 v82, v207, v80
	v_mov_b32_e32 v89, v87
	v_pk_add_f32 v[86:87], v[90:91], v[88:89]
	v_pk_fma_f32 v[88:89], v[36:37], v[36:37], v[84:85] op_sel_hi:[1,1,0]
	v_mul_f32_e32 v84, v38, v38
	s_waitcnt lgkmcnt(0)
	v_pk_add_f32 v[80:81], v[80:81], v[82:83]
	ds_bpermute_b32 v83, v206, v81
	ds_bpermute_b32 v82, v206, v80
	v_pk_add_f32 v[86:87], v[86:87], v[86:87] op_sel_hi:[0,1]
	v_pk_fma_f32 v[90:91], v[38:39], v[38:39], v[84:85] op_sel_hi:[1,1,0]
	v_mul_f32_e32 v84, v34, v34
	v_mul_f32_e32 v86, v35, v35
	s_waitcnt lgkmcnt(0)
	v_pk_add_f32 v[80:81], v[80:81], v[82:83]
	ds_bpermute_b32 v83, v205, v81
	ds_bpermute_b32 v82, v205, v80
	v_mul_f32_e32 v88, v32, v32
	v_mul_f32_e32 v90, v33, v33
	v_pk_add_f32 v[84:85], v[84:85], v[86:87]
	v_pk_add_f32 v[86:87], v[88:89], v[90:91]
	v_pk_mul_f32 v[88:89], v[26:27], v[26:27]
	v_pk_add_f32 v[86:87], v[84:85], v[86:87]
	v_pk_mul_f32 v[84:85], v[30:31], v[30:31]
	s_waitcnt lgkmcnt(0)
	v_pk_add_f32 v[80:81], v[80:81], v[82:83]
	v_pk_mov_b32 v[90:91], v[88:89], v[84:85] op_sel:[1,0]
	v_mov_b32_e32 v89, v85
	v_pk_add_f32 v[84:85], v[90:91], v[88:89]
	v_pk_mul_f32 v[88:89], v[28:29], v[28:29]
	v_pk_mul_f32 v[90:91], v[24:25], v[24:25]
	ds_bpermute_b32 v83, v203, v81
	ds_bpermute_b32 v82, v203, v80
	v_pk_add_f32 v[84:85], v[84:85], v[84:85] op_sel_hi:[0,1]
	v_pk_mov_b32 v[92:93], v[90:91], v[88:89] op_sel:[1,0]
	v_mov_b32_e32 v91, v89
	v_pk_add_f32 v[88:89], v[92:93], v[90:91]
	v_mul_f32_e32 v84, v20, v20
	v_pk_add_f32 v[88:89], v[88:89], v[88:89] op_sel_hi:[0,1]
	v_pk_fma_f32 v[90:91], v[20:21], v[20:21], v[84:85] op_sel_hi:[1,1,0]
	v_mul_f32_e32 v84, v22, v22
	v_pk_fma_f32 v[92:93], v[22:23], v[22:23], v[84:85] op_sel_hi:[1,1,0]
	v_mul_f32_e32 v84, v18, v18
	v_mul_f32_e32 v88, v19, v19
	v_pk_add_f32 v[84:85], v[84:85], v[88:89]
	s_waitcnt lgkmcnt(0)
	v_pk_add_f32 v[80:81], v[80:81], v[82:83]
	v_mov_b64_e32 v[88:89], s[28:29]
	v_pk_fma_f32 v[94:95], v[80:81], s[26:27], v[88:89] op_sel_hi:[1,0,0]
	v_mul_f32_e32 v90, v16, v16
	v_mul_f32_e32 v80, 0x4b800000, v95
	v_cmp_gt_f32_e32 vcc, s17, v95
	v_mul_f32_e32 v92, v17, v17
	s_nop 0
	v_cndmask_b32_e32 v80, v95, v80, vcc
	v_rsq_f32_e32 v82, v80
	v_pk_add_f32 v[80:81], v[90:91], v[92:93]
	v_lshl_add_u64 v[92:93], s[18:19], 0, v[148:149]
	v_pk_add_f32 v[90:91], v[84:85], v[80:81]
	v_mul_f32_e32 v80, 0x45800000, v82
	v_cndmask_b32_e32 v98, v82, v80, vcc
	v_pk_mul_f32 v[80:81], v[98:99], v[66:67] op_sel_hi:[0,1]
	v_pk_mul_f32 v[76:77], v[98:99], v[76:77] op_sel_hi:[0,1]
	v_pk_mul_f32 v[66:67], v[98:99], v[78:79] op_sel_hi:[0,1]
	v_pk_mul_f32 v[78:79], v[0:1], v[80:81]
	v_pk_mul_f32 v[80:81], v[10:11], v[76:77]
	v_add_co_u32_e32 v76, vcc, s23, v92
	v_pk_mul_f32 v[70:71], v[98:99], v[70:71] op_sel_hi:[0,1]
	s_nop 0
	v_addc_co_u32_e32 v77, vcc, 0, v93, vcc
	v_add_co_u32_e32 v92, vcc, s27, v92
	v_pk_mul_f32 v[72:73], v[98:99], v[72:73] op_sel_hi:[0,1]
	s_nop 0
	v_addc_co_u32_e32 v93, vcc, 0, v93, vcc
	v_pk_mul_f32 v[74:75], v[98:99], v[74:75] op_sel_hi:[0,1]
	v_pk_mul_f32 v[68:69], v[98:99], v[68:69] op_sel_hi:[0,1]
	v_pk_mul_f32 v[124:125], v[4:5], v[70:71]
	v_mul_f32_e32 v70, 0x4b800000, v94
	v_cmp_gt_f32_e32 vcc, s17, v94
	v_pk_mul_f32 v[112:113], v[14:15], v[74:75]
	v_pk_mul_f32 v[96:97], v[12:13], v[72:73]
	v_pk_mul_f32 v[166:167], v[6:7], v[68:69]
	v_cndmask_b32_e32 v70, v94, v70, vcc
	v_cvt_pk_bf16_f32 v68, v96, v97
	v_cvt_pk_bf16_f32 v69, v112, v113
	v_rsq_f32_e32 v72, v70
	v_cvt_pk_bf16_f32 v70, v124, v125
	v_cvt_pk_bf16_f32 v71, v166, v167
	global_store_dwordx4 v[76:77], v[68:71], off offset:1024
	v_mul_f32_e32 v73, 0x45800000, v72
	v_cndmask_b32_e32 v72, v72, v73, vcc
	v_mov_b32_e32 v68, v90
	v_mov_b32_e32 v69, v86
	v_mov_b32_e32 v86, v91
	v_pk_add_f32 v[68:69], v[68:69], v[86:87]
	ds_bpermute_b32 v71, v209, v69
	ds_bpermute_b32 v70, v209, v68
	v_pk_mul_f32 v[62:63], v[72:73], v[62:63] op_sel_hi:[0,1]
	v_pk_mul_f32 v[198:199], v[2:3], v[62:63]
	v_pk_mul_f32 v[60:61], v[72:73], v[60:61] op_sel_hi:[0,1]
	v_pk_mul_f32 v[200:201], v[0:1], v[60:61]
	s_waitcnt lgkmcnt(0)
	v_pk_add_f32 v[62:63], v[68:69], v[70:71]
	ds_bpermute_b32 v69, v208, v63
	ds_bpermute_b32 v68, v208, v62
	v_pk_mul_f32 v[56:57], v[72:73], v[56:57] op_sel_hi:[0,1]
	v_pk_mul_f32 v[58:59], v[72:73], v[58:59] op_sel_hi:[0,1]
	v_pk_mul_f32 v[194:195], v[10:11], v[58:59]
	v_pk_mul_f32 v[196:197], v[8:9], v[56:57]
	s_waitcnt lgkmcnt(0)
	v_pk_add_f32 v[60:61], v[62:63], v[68:69]
	ds_bpermute_b32 v63, v207, v61
	ds_bpermute_b32 v62, v207, v60
	v_cvt_pk_bf16_f32 v56, v200, v201
	v_cvt_pk_bf16_f32 v57, v198, v199
	v_cvt_pk_bf16_f32 v58, v196, v197
	v_cvt_pk_bf16_f32 v59, v194, v195
	s_waitcnt lgkmcnt(0)
	v_pk_add_f32 v[60:61], v[60:61], v[62:63]
	ds_bpermute_b32 v63, v206, v61
	ds_bpermute_b32 v62, v206, v60
	global_store_dwordx4 v[76:77], v[56:59], off offset:2048
	v_pk_mul_f32 v[52:53], v[72:73], v[52:53] op_sel_hi:[0,1]
	v_pk_mul_f32 v[54:55], v[72:73], v[54:55] op_sel_hi:[0,1]
	v_pk_mul_f32 v[192:193], v[12:13], v[52:53]
	s_waitcnt lgkmcnt(0)
	v_pk_add_f32 v[56:57], v[60:61], v[62:63]
	ds_bpermute_b32 v59, v205, v57
	ds_bpermute_b32 v58, v205, v56
	v_pk_mul_f32 v[190:191], v[14:15], v[54:55]
	v_pk_mul_f32 v[50:51], v[72:73], v[50:51] op_sel_hi:[0,1]
	v_pk_mul_f32 v[188:189], v[4:5], v[50:51]
	v_pk_mul_f32 v[48:49], v[72:73], v[48:49] op_sel_hi:[0,1]
	s_waitcnt lgkmcnt(0)
; #define LAS __attribute__((address_space(3)))
; #define GAS __attribute__((address_space(1)))
; template <int MODE, bool XBF>
; __device__ __forceinline__ void rmsnorm_rows(const void* x, const float* gain, bf16_t* H, int gw, int NGW, int lane, const LAS float* WF, const float* fbias, float* LF) {
;     ...
;         for (int r = 0; r < RB; ++r) {
;             const int row = row0 + r;
;             const float rstd = rsqrtf(s[r] * (1.f / D) + 1e-6f);
;             const size_t hrow = MODE == 2 ? (size_t)row + (row >> 12) + 1 : (size_t)row;
; #pragma unroll
;             for (int j = 0; j < 2; ++j) { v[r][j][0] = v[r][j][0] * rstd * g[j][0]; v[r][j][1] = v[r][j][1] * rstd * g[j][1];
;                 *(GAS u32x4*)(H + hrow * D + 512 * j + lane * 8) = pack8(v[r][j][0], v[r][j][1]); }
;         }
;         if (MODE == 1) {
;             float dt[RB][8];
; #pragma unroll
;             for (int r = 0; r < RB; ++r)
; #pragma unroll
;                 for (int h = 0; h < 8; ++h) dt[r][h] = 0.f;
; #pragma unroll
;             for (int j = 0; j < 2; ++j)
; #pragma unroll
;                 for (int e = 0; e < 2; ++e)
; #pragma unroll
;                     for (int c = 0; c < 4; ++c) {
;                         const LAS float* wp = WF + (512 * j + lane * 8 + 4 * e + c) * 8;
;                         const f32x4 w0 = *(const LAS f32x4*)wp, w1 = *(const LAS f32x4*)(wp + 4);
; #pragma unroll
;                         for (int r = 0; r < RB; ++r) {
;                             const float hv = v[r][j][e][c];
;                             dt[r][0] += hv * w0[0]; dt[r][1] += hv * w0[1]; dt[r][2] += hv * w0[2]; dt[r][3] += hv * w0[3];
;                             dt[r][4] += hv * w1[0]; dt[r][5] += hv * w1[1]; dt[r][6] += hv * w1[2]; dt[r][7] += hv * w1[3];
;                         }
	v_pk_add_f32 v[52:53], v[56:57], v[58:59]
	ds_bpermute_b32 v55, v203, v53
	ds_bpermute_b32 v54, v203, v52
	v_pk_mul_f32 v[186:187], v[6:7], v[48:49]
	v_cvt_pk_bf16_f32 v48, v192, v193
	v_cvt_pk_bf16_f32 v49, v190, v191
	v_pk_mul_f32 v[64:65], v[98:99], v[64:65] op_sel_hi:[0,1]
	s_waitcnt lgkmcnt(0)
	v_pk_add_f32 v[50:51], v[52:53], v[54:55]
	v_pk_mul_f32 v[66:67], v[2:3], v[66:67]
	v_pk_fma_f32 v[52:53], v[50:51], s[26:27], v[88:89] op_sel_hi:[1,0,0]
	v_cvt_pk_bf16_f32 v51, v186, v187
	v_mul_f32_e32 v50, 0x4b800000, v53
	v_cmp_gt_f32_e32 vcc, s17, v53
	v_pk_mul_f32 v[64:65], v[8:9], v[64:65]
	v_cvt_pk_bf16_f32 v82, v78, v79
	v_cndmask_b32_e32 v50, v53, v50, vcc
	v_rsq_f32_e32 v53, v50
	v_cvt_pk_bf16_f32 v50, v188, v189
	global_store_dwordx4 v[76:77], v[48:51], off offset:3072
	v_cvt_pk_bf16_f32 v83, v66, v67
	v_cvt_pk_bf16_f32 v84, v64, v65
	v_mul_f32_e32 v48, 0x45800000, v53
	v_cndmask_b32_e32 v48, v53, v48, vcc
	v_pk_mul_f32 v[34:35], v[48:49], v[34:35] op_sel_hi:[0,1]
	v_pk_mul_f32 v[172:173], v[4:5], v[34:35]
	v_mul_f32_e32 v34, 0x4b800000, v52
	v_cmp_gt_f32_e32 vcc, s17, v52
	v_pk_mul_f32 v[36:37], v[48:49], v[36:37] op_sel_hi:[0,1]
	v_pk_mul_f32 v[176:177], v[12:13], v[36:37]
	v_cndmask_b32_e32 v34, v52, v34, vcc
	v_rsq_f32_e32 v36, v34
	v_pk_mul_f32 v[38:39], v[48:49], v[38:39] op_sel_hi:[0,1]
	v_pk_mul_f32 v[32:33], v[48:49], v[32:33] op_sel_hi:[0,1]
	v_pk_mul_f32 v[174:175], v[14:15], v[38:39]
	v_pk_mul_f32 v[170:171], v[6:7], v[32:33]
	v_cvt_pk_bf16_f32 v32, v176, v177
	v_cvt_pk_bf16_f32 v33, v174, v175
	v_cvt_pk_bf16_f32 v34, v172, v173
	v_cvt_pk_bf16_f32 v35, v170, v171
	global_store_dwordx4 v[92:93], v[32:35], off offset:1024
	v_pk_mul_f32 v[42:43], v[48:49], v[42:43] op_sel_hi:[0,1]
	v_pk_mul_f32 v[46:47], v[48:49], v[46:47] op_sel_hi:[0,1]
	v_mul_f32_e32 v32, 0x45800000, v36
	v_cndmask_b32_e32 v32, v36, v32, vcc
	v_pk_mul_f32 v[26:27], v[32:33], v[26:27] op_sel_hi:[0,1]
	v_pk_mul_f32 v[184:185], v[0:1], v[42:43]
	v_pk_mul_f32 v[40:41], v[48:49], v[40:41] op_sel_hi:[0,1]
	v_pk_mul_f32 v[42:43], v[48:49], v[44:45] op_sel_hi:[0,1]
	v_pk_mul_f32 v[30:31], v[32:33], v[30:31] op_sel_hi:[0,1]
	v_pk_mul_f32 v[168:169], v[0:1], v[26:27]
	v_pk_mul_f32 v[24:25], v[32:33], v[24:25] op_sel_hi:[0,1]
	v_pk_mul_f32 v[26:27], v[32:33], v[28:29] op_sel_hi:[0,1]
	v_pk_mul_f32 v[20:21], v[32:33], v[20:21] op_sel_hi:[0,1]
	v_pk_mul_f32 v[22:23], v[32:33], v[22:23] op_sel_hi:[0,1]
	v_pk_mul_f32 v[18:19], v[32:33], v[18:19] op_sel_hi:[0,1]
	v_pk_mul_f32 v[16:17], v[32:33], v[16:17] op_sel_hi:[0,1]
	v_pk_mul_f32 v[182:183], v[2:3], v[46:47]
	v_pk_mul_f32 v[178:179], v[10:11], v[42:43]
	v_pk_mul_f32 v[180:181], v[8:9], v[40:41]
	v_pk_mul_f32 v[164:165], v[2:3], v[30:31]
	v_pk_mul_f32 v[160:161], v[10:11], v[26:27]
	v_pk_mul_f32 v[162:163], v[8:9], v[24:25]
	v_pk_mul_f32 v[156:157], v[14:15], v[22:23]
	v_pk_mul_f32 v[158:159], v[12:13], v[20:21]
	v_pk_mul_f32 v[152:153], v[6:7], v[16:17]
	v_pk_mul_f32 v[154:155], v[4:5], v[18:19]
	v_cvt_pk_bf16_f32 v85, v80, v81
	v_cvt_pk_bf16_f32 v40, v184, v185
	v_cvt_pk_bf16_f32 v41, v182, v183
	v_cvt_pk_bf16_f32 v42, v180, v181
	v_cvt_pk_bf16_f32 v43, v178, v179
	v_cvt_pk_bf16_f32 v24, v168, v169
	v_cvt_pk_bf16_f32 v25, v164, v165
	v_cvt_pk_bf16_f32 v26, v162, v163
	v_cvt_pk_bf16_f32 v27, v160, v161
	v_cvt_pk_bf16_f32 v16, v158, v159
	v_cvt_pk_bf16_f32 v17, v156, v157
	v_cvt_pk_bf16_f32 v18, v154, v155
	v_cvt_pk_bf16_f32 v19, v152, v153
	global_store_dwordx4 v[92:93], v[82:85], off offset:-4096
	global_store_dwordx4 v[92:93], v[40:43], off
	global_store_dwordx4 v[92:93], v[24:27], off offset:2048
	ds_read_b128 v[32:35], v210
	global_store_dwordx4 v[92:93], v[16:19], off offset:3072
	ds_read_b128 v[28:31], v210 offset:16
	ds_read_b128 v[20:23], v210 offset:32
	ds_read_b128 v[16:19], v210 offset:48
	ds_read_b128 v[36:39], v210 offset:64
	ds_read_b128 v[24:27], v210 offset:80
	ds_read_b128 v[44:47], v210 offset:96
	ds_read_b128 v[40:43], v210 offset:112
	ds_read_b128 v[52:55], v210 offset:128
	ds_read_b128 v[48:51], v210 offset:144
	s_waitcnt lgkmcnt(9)
	v_fma_f32 v151, v32, v78, 0
	v_fma_f32 v204, v33, v78, 0
	v_fma_f32 v216, v34, v78, 0
	v_fma_f32 v217, v35, v78, 0
	s_waitcnt lgkmcnt(8)
	v_fma_f32 v218, v28, v78, 0
	v_fma_f32 v219, v29, v78, 0
	v_fma_f32 v220, v30, v78, 0
	v_fma_f32 v221, v31, v78, 0
	ds_read_b128 v[60:63], v210 offset:160
	ds_read_b128 v[56:59], v210 offset:176
	s_waitcnt lgkmcnt(9)
	v_fmac_f32_e32 v151, v79, v20
	v_fmac_f32_e32 v204, v79, v21
	v_fmac_f32_e32 v216, v79, v22
	v_fmac_f32_e32 v217, v79, v23
	s_waitcnt lgkmcnt(8)
	v_fmac_f32_e32 v218, v79, v16
	v_fmac_f32_e32 v219, v79, v17
	v_fmac_f32_e32 v220, v79, v18
	v_fmac_f32_e32 v221, v79, v19
	flat_load_dword v215, v[144:145] offset:32
	s_waitcnt lgkmcnt(0)
	v_fmac_f32_e32 v151, v66, v36
	v_fmac_f32_e32 v204, v66, v37
	v_fmac_f32_e32 v216, v66, v38
	v_fmac_f32_e32 v217, v66, v39
	v_fmac_f32_e32 v218, v66, v24
	v_fmac_f32_e32 v219, v66, v25
	v_fmac_f32_e32 v220, v66, v26
	v_fmac_f32_e32 v221, v66, v27
	v_fmac_f32_e32 v151, v67, v44
	v_fmac_f32_e32 v204, v67, v45
	v_fmac_f32_e32 v216, v67, v46
	v_fmac_f32_e32 v217, v67, v47
	v_fmac_f32_e32 v218, v67, v40
	v_fmac_f32_e32 v219, v67, v41
	v_fmac_f32_e32 v220, v67, v42
	v_fmac_f32_e32 v221, v67, v43
	v_fmac_f32_e32 v151, v64, v52
	v_fmac_f32_e32 v204, v64, v53
	v_fmac_f32_e32 v216, v64, v54
	v_fmac_f32_e32 v217, v64, v55
	v_fmac_f32_e32 v218, v64, v48
	v_fmac_f32_e32 v219, v64, v49
	v_fmac_f32_e32 v220, v64, v50
	v_fmac_f32_e32 v221, v64, v51
	v_fmac_f32_e32 v151, v65, v60
	v_fmac_f32_e32 v204, v65, v61
	v_fmac_f32_e32 v216, v65, v62
	v_fmac_f32_e32 v217, v65, v63
	v_fmac_f32_e32 v218, v65, v56
	ds_read_b128 v[68:71], v210 offset:192
	v_fmac_f32_e32 v219, v65, v57
	v_fmac_f32_e32 v220, v65, v58
	v_fmac_f32_e32 v221, v65, v59
	ds_read_b128 v[64:67], v210 offset:208
	ds_read_b128 v[76:79], v210 offset:224
	ds_read_b128 v[72:75], v210 offset:240
	s_waitcnt lgkmcnt(0)
; #define LAS __attribute__((address_space(3)))
; template <int MODE, bool XBF>
; __device__ __forceinline__ void rmsnorm_rows(const void* x, const float* gain, bf16_t* H, int gw, int NGW, int lane, const LAS float* WF, const float* fbias, float* LF) {
;     ...
;             for (int j = 0; j < 2; ++j)
; #pragma unroll
;                 for (int e = 0; e < 2; ++e)
; #pragma unroll
;                     for (int c = 0; c < 4; ++c) {
;                         const LAS float* wp = WF + (512 * j + lane * 8 + 4 * e + c) * 8;
;                         const f32x4 w0 = *(const LAS f32x4*)wp, w1 = *(const LAS f32x4*)(wp + 4);
; #pragma unroll
;                         for (int r = 0; r < RB; ++r) {
;                             const float hv = v[r][j][e][c];
;                             dt[r][0] += hv * w0[0]; dt[r][1] += hv * w0[1]; dt[r][2] += hv * w0[2]; dt[r][3] += hv * w0[3];
;                             dt[r][4] += hv * w1[0]; dt[r][5] += hv * w1[1]; dt[r][6] += hv * w1[2]; dt[r][7] += hv * w1[3];
;                         }
;                     }
;             const bool hi32 = (lane & 32) != 0, hi16 = (lane & 16) != 0, hi8 = (lane & 8) != 0;
;             const int hsel = (hi32 ? 4 : 0) + (hi16 ? 2 : 0) + (hi8 ? 1 : 0);
;             const float fb = fbias[hsel];
; #pragma unroll
;             for (int r = 0; r < RB; ++r) {
;                 float d4[4], d2[2], d1;
; #pragma unroll
;                 for (int k = 0; k < 4; ++k) { const float send = hi32 ? dt[r][k] : dt[r][k + 4], keep = hi32 ? dt[r][k + 4] : dt[r][k]; d4[k] = keep + __shfl_xor(send, 32); }
; #pragma unroll
;                 for (int k = 0; k < 2; ++k) { const float send = hi16 ? d4[k] : d4[k + 2], keep = hi16 ? d4[k + 2] : d4[k]; d2[k] = keep + __shfl_xor(send, 16); }
;                 { const float send = hi8 ? d2[0] : d2[1], keep = hi8 ? d2[1] : d2[0]; d1 = keep + __shfl_xor(send, 8); }
;                 d1 += __shfl_xor(d1, 4); d1 += __shfl_xor(d1, 2); d1 += __shfl_xor(d1, 1);
	v_fmac_f32_e32 v151, v80, v68
	v_fmac_f32_e32 v204, v80, v69
	v_fmac_f32_e32 v216, v80, v70
	v_fmac_f32_e32 v217, v80, v71
	v_fmac_f32_e32 v218, v80, v64
	v_fmac_f32_e32 v219, v80, v65
	v_fmac_f32_e32 v220, v80, v66
	v_fmac_f32_e32 v221, v80, v67
	v_fmac_f32_e32 v151, v81, v76
	v_fmac_f32_e32 v204, v81, v77
	v_fmac_f32_e32 v216, v81, v78
	v_fmac_f32_e32 v217, v81, v79
	v_fmac_f32_e32 v218, v81, v72
	ds_read_b128 v[84:87], v210 offset:17408
	v_fmac_f32_e32 v219, v81, v73
	v_fmac_f32_e32 v220, v81, v74
	v_fmac_f32_e32 v221, v81, v75
	ds_read_b128 v[80:83], v210 offset:17424
	ds_read_b128 v[92:95], v210 offset:17440
	ds_read_b128 v[88:91], v210 offset:17456
	s_waitcnt lgkmcnt(0)
	v_fmac_f32_e32 v151, v96, v84
	v_fmac_f32_e32 v204, v96, v85
	v_fmac_f32_e32 v216, v96, v86
	v_fmac_f32_e32 v217, v96, v87
	v_fmac_f32_e32 v218, v96, v80
	v_fmac_f32_e32 v219, v96, v81
	v_fmac_f32_e32 v220, v96, v82
	v_fmac_f32_e32 v221, v96, v83
	v_fmac_f32_e32 v151, v97, v92
	v_fmac_f32_e32 v204, v97, v93
	v_fmac_f32_e32 v216, v97, v94
	v_fmac_f32_e32 v217, v97, v95
	v_fmac_f32_e32 v218, v97, v88
	ds_read_b128 v[100:103], v210 offset:17472
	v_fmac_f32_e32 v219, v97, v89
	v_fmac_f32_e32 v220, v97, v90
	v_fmac_f32_e32 v221, v97, v91
	ds_read_b128 v[96:99], v210 offset:17488
	ds_read_b128 v[108:111], v210 offset:17504
	ds_read_b128 v[104:107], v210 offset:17520
	s_waitcnt lgkmcnt(0)
	v_fmac_f32_e32 v151, v112, v100
	v_fmac_f32_e32 v204, v112, v101
	v_fmac_f32_e32 v216, v112, v102
	v_fmac_f32_e32 v217, v112, v103
	v_fmac_f32_e32 v218, v112, v96
	v_fmac_f32_e32 v219, v112, v97
	v_fmac_f32_e32 v220, v112, v98
	v_fmac_f32_e32 v221, v112, v99
	v_fmac_f32_e32 v151, v113, v108
	v_fmac_f32_e32 v204, v113, v109
	v_fmac_f32_e32 v216, v113, v110
	v_fmac_f32_e32 v217, v113, v111
	v_fmac_f32_e32 v218, v113, v104
	ds_read_b128 v[116:119], v210 offset:17536
	v_fmac_f32_e32 v219, v113, v105
	v_fmac_f32_e32 v220, v113, v106
	v_fmac_f32_e32 v221, v113, v107
	ds_read_b128 v[112:115], v210 offset:17552
	ds_read_b128 v[120:123], v210 offset:17568
	ds_read_b128 v[140:143], v210 offset:17584
	s_waitcnt lgkmcnt(0)
	v_fmac_f32_e32 v151, v124, v116
	v_fmac_f32_e32 v204, v124, v117
	v_fmac_f32_e32 v216, v124, v118
	v_fmac_f32_e32 v217, v124, v119
	v_fmac_f32_e32 v218, v124, v112
	v_fmac_f32_e32 v219, v124, v113
	v_fmac_f32_e32 v220, v124, v114
	v_fmac_f32_e32 v221, v124, v115
	ds_read_b128 v[136:139], v210 offset:17600
	ds_read_b128 v[132:135], v210 offset:17616
	v_fmac_f32_e32 v151, v125, v120
	v_fmac_f32_e32 v204, v125, v121
	v_fmac_f32_e32 v216, v125, v122
	v_fmac_f32_e32 v217, v125, v123
	v_fmac_f32_e32 v218, v125, v140
	v_fmac_f32_e32 v219, v125, v141
	v_fmac_f32_e32 v220, v125, v142
	v_fmac_f32_e32 v221, v125, v143
	ds_read_b128 v[128:131], v210 offset:17632
	ds_read_b128 v[124:127], v210 offset:17648
	s_waitcnt lgkmcnt(0)
	v_fmac_f32_e32 v151, v166, v136
	v_fmac_f32_e32 v218, v166, v132
	v_fmac_f32_e32 v204, v166, v137
	v_fmac_f32_e32 v151, v167, v128
	v_fmac_f32_e32 v218, v167, v124
	v_fmac_f32_e32 v216, v166, v138
	v_fmac_f32_e32 v217, v166, v139
	v_fmac_f32_e32 v219, v166, v133
	v_fmac_f32_e32 v220, v166, v134
	v_fmac_f32_e32 v221, v166, v135
	v_cndmask_b32_e64 v166, v151, v218, s[2:3]
	ds_bpermute_b32 v166, v203, v166
	v_fmac_f32_e32 v204, v167, v129
	v_fmac_f32_e32 v219, v167, v125
	v_cndmask_b32_e64 v151, v218, v151, s[2:3]
	v_fmac_f32_e32 v216, v167, v130
	v_fmac_f32_e32 v220, v167, v126
	s_waitcnt lgkmcnt(0)
	v_add_f32_e32 v151, v151, v166
	v_cndmask_b32_e64 v166, v204, v219, s[2:3]
	v_fmac_f32_e32 v217, v167, v131
	v_fmac_f32_e32 v221, v167, v127
	v_cndmask_b32_e64 v167, v219, v204, s[2:3]
	ds_bpermute_b32 v166, v203, v166
	v_cndmask_b32_e64 v204, v216, v220, s[2:3]
	ds_bpermute_b32 v204, v203, v204
	v_cndmask_b32_e64 v218, v217, v221, s[2:3]
	ds_bpermute_b32 v218, v203, v218
	s_waitcnt lgkmcnt(0)
	v_add_f32_e32 v166, v167, v166
	v_cndmask_b32_e64 v167, v220, v216, s[2:3]
	v_add_f32_e32 v167, v167, v204
	v_cndmask_b32_e64 v204, v221, v217, s[2:3]
	v_add_f32_e32 v204, v204, v218
	v_cndmask_b32_e64 v216, v151, v167, s[4:5]
	v_cndmask_b32_e64 v217, v166, v204, s[4:5]
	ds_bpermute_b32 v216, v205, v216
	ds_bpermute_b32 v217, v205, v217
	v_cndmask_b32_e64 v151, v167, v151, s[4:5]
	v_cndmask_b32_e64 v166, v204, v166, s[4:5]
	s_waitcnt lgkmcnt(0)
	v_add_f32_e32 v151, v151, v216
	v_add_f32_e32 v166, v166, v217
	v_cndmask_b32_e64 v167, v151, v166, s[6:7]
	ds_bpermute_b32 v167, v206, v167
	v_cndmask_b32_e64 v151, v166, v151, s[6:7]
	s_waitcnt lgkmcnt(0)
	v_add_f32_e32 v151, v151, v167
	ds_bpermute_b32 v166, v207, v151
	s_waitcnt lgkmcnt(0)
	v_add_f32_e32 v151, v151, v166
	ds_bpermute_b32 v166, v208, v151
	s_waitcnt lgkmcnt(0)
	v_add_f32_e32 v151, v151, v166
	ds_bpermute_b32 v216, v209, v151
	v_lshl_add_u64 v[166:167], v[146:147], 0, s[30:31]
	s_and_saveexec_b64 s[30:31], s[8:9]
	s_cbranch_execz .LBB0_1684
; template <int MODE, bool XBF>
; __device__ __forceinline__ void rmsnorm_rows(const void* x, const float* gain, bf16_t* H, int gw, int NGW, int lane, const LAS float* WF, const float* fbias, float* LF) {
;     ...
;                 if ((lane & 7) == 0) {
;                     const int row = row0 + r;
;                     const float z = d1 + fb;
;                     LF[((size_t)(row >> 12) * 8 + hsel) * S + (row & 4095)] = fminf(z, 0.f) - log1pf(__expf(-fabsf(z)));
;                 }
	s_waitcnt lgkmcnt(0)
	v_add_f32_e32 v151, v151, v216
	s_waitcnt vmcnt(0)
	v_add_f32_e32 v151, v215, v151
	v_mul_f32_e64 v204, |v151|, s29
	v_exp_f32_e32 v204, v204
	v_min_f32_e32 v230, 0, v151
	s_lshl_b32 s12, s40, 2
	v_add_f32_e32 v151, 1.0, v204
	v_add_f32_e32 v216, -1.0, v151
	v_sub_f32_e32 v217, v216, v151
	v_sub_f32_e32 v216, v204, v216
	v_add_f32_e32 v217, 1.0, v217
	v_frexp_mant_f32_e32 v218, v151
	v_add_f32_e32 v219, v216, v217
	v_cvt_f64_f32_e32 v[216:217], v151
	v_frexp_exp_i32_f64_e32 v216, v[216:217]
	v_cmp_gt_f32_e32 vcc, s34, v218
	s_nop 1
	v_subbrev_co_u32_e32 v224, vcc, 0, v216, vcc
	v_sub_u32_e32 v216, 0, v224
	v_ldexp_f32 v151, v151, v216
	v_add_f32_e32 v218, -1.0, v151
	v_add_f32_e32 v217, 1.0, v218
	v_ldexp_f32 v216, v219, v216
	v_sub_f32_e32 v217, v151, v217
	v_add_f32_e32 v219, v216, v217
	v_add_f32_e32 v217, 1.0, v151
	v_add_f32_e32 v220, -1.0, v217
	v_sub_f32_e32 v151, v151, v220
	v_add_f32_e32 v151, v216, v151
	v_add_f32_e32 v225, v217, v151
	v_rcp_f32_e32 v226, v225
	v_sub_f32_e32 v216, v225, v217
	v_add_f32_e32 v217, v218, v219
	v_sub_f32_e32 v151, v151, v216
	v_mul_f32_e32 v228, v217, v226
	v_sub_f32_e32 v216, v217, v218
	v_mul_f32_e32 v218, v225, v228
	v_fma_f32 v220, v228, v225, -v218
	v_fmac_f32_e32 v220, v228, v151
	v_sub_f32_e32 v227, v219, v216
	v_add_f32_e32 v216, v218, v220
	v_sub_f32_e32 v219, v217, v216
	v_pk_add_f32 v[222:223], v[216:217], v[218:219] neg_lo:[0,1] neg_hi:[0,1]
	v_mov_b32_e32 v221, v216
	v_pk_add_f32 v[216:217], v[222:223], v[220:221] neg_lo:[0,1] neg_hi:[0,1]
	v_cmp_neq_f32_e32 vcc, s38, v204
	v_add_f32_e32 v217, v227, v217
	v_add_f32_e32 v216, v216, v217
	v_add_f32_e32 v217, v219, v216
	v_mul_f32_e32 v227, v226, v217
	v_mul_f32_e32 v218, v225, v227
	v_fma_f32 v220, v227, v225, -v218
	v_fmac_f32_e32 v220, v227, v151
	v_sub_f32_e32 v151, v219, v217
	v_add_f32_e32 v151, v216, v151
	v_add_f32_e32 v216, v218, v220
	v_sub_f32_e32 v219, v217, v216
	v_pk_add_f32 v[222:223], v[216:217], v[218:219] neg_lo:[0,1] neg_hi:[0,1]
	v_mov_b32_e32 v221, v216
	v_pk_add_f32 v[216:217], v[222:223], v[220:221] neg_lo:[0,1] neg_hi:[0,1]
	s_nop 0
	v_add_f32_e32 v151, v151, v217
	v_add_f32_e32 v151, v216, v151
	v_add_f32_e32 v217, v228, v227
	v_add_f32_e32 v151, v219, v151
	v_sub_f32_e32 v216, v217, v228
	v_mul_f32_e32 v151, v226, v151
	v_sub_f32_e32 v216, v227, v216
	v_add_f32_e32 v218, v216, v151
	v_add_f32_e32 v220, v217, v218
	v_cvt_f32_i32_e32 v216, v224
	v_mul_f32_e32 v221, v220, v220
	v_sub_f32_e32 v217, v220, v217
	v_fmamk_f32 v151, v221, 0x3e9b6dac, v211
	v_sub_f32_e32 v217, v218, v217
	v_fmaak_f32 v151, v221, v151, 0x3f2aaada
	v_ldexp_f32 v222, v217, 1
	v_mul_f32_e32 v217, v220, v221
	v_ldexp_f32 v219, v220, 1
	v_pk_mul_f32 v[220:221], v[216:217], v[150:151]
	s_nop 0
	v_fma_f32 v218, v216, s35, -v220
	v_fmac_f32_e32 v218, 0xb102e308, v216
	v_pk_add_f32 v[216:217], v[220:221], v[218:219]
	s_nop 0
	v_sub_f32_e32 v151, v217, v219
	v_sub_f32_e32 v151, v221, v151
	v_add_f32_e32 v223, v222, v151
	v_mov_b32_e32 v222, v220
	v_pk_add_f32 v[220:221], v[216:217], v[220:221] neg_lo:[0,1] neg_hi:[0,1]
	v_pk_add_f32 v[224:225], v[216:217], v[222:223]
	v_mov_b32_e32 v219, v216
	v_mov_b32_e32 v221, v225
	v_pk_add_f32 v[226:227], v[218:219], v[220:221] neg_lo:[0,1] neg_hi:[0,1]
	v_pk_add_f32 v[218:219], v[218:219], v[220:221]
	v_mov_b32_e32 v222, v223
	v_pk_add_f32 v[220:221], v[218:219], v[216:217] op_sel:[1,0] op_sel_hi:[0,1] neg_lo:[0,1] neg_hi:[0,1]
	v_pk_add_f32 v[228:229], v[224:225], v[220:221] op_sel_hi:[1,0] neg_lo:[0,1] neg_hi:[0,1]
	v_mov_b32_e32 v224, v225
	v_mov_b32_e32 v225, v219
	v_pk_mov_b32 v[220:221], v[216:217], v[220:221] op_sel:[1,0]
	v_mov_b32_e32 v223, v216
	v_pk_add_f32 v[220:221], v[224:225], v[220:221] neg_lo:[0,1] neg_hi:[0,1]
	v_mov_b32_e32 v228, v226
	v_pk_add_f32 v[216:217], v[222:223], v[220:221] neg_lo:[0,1] neg_hi:[0,1]
	v_mov_b32_e32 v227, v219
	v_pk_add_f32 v[220:221], v[228:229], v[216:217]
	s_nop 0
	v_pk_add_f32 v[222:223], v[220:221], v[220:221] op_sel:[0,1] op_sel_hi:[1,0]
	s_nop 0
	v_pk_add_f32 v[218:219], v[218:219], v[222:223] op_sel:[1,0] op_sel_hi:[0,1]
	v_mov_b32_e32 v221, v218
	v_pk_add_f32 v[224:225], v[220:221], v[226:227] neg_lo:[0,1] neg_hi:[0,1]
	v_mov_b32_e32 v217, v222
	v_sub_f32_e32 v151, v220, v224
	v_pk_add_f32 v[216:217], v[216:217], v[224:225] neg_lo:[0,1] neg_hi:[0,1]
	v_sub_f32_e32 v151, v226, v151
	v_add_f32_e32 v151, v216, v151
	v_add_f32_e32 v151, v151, v217
	v_add_f32_e32 v151, v218, v151
	v_cndmask_b32_e32 v151, v212, v151, vcc
	v_cmp_ngt_f32_e32 vcc, -1.0, v204
	v_lshl_add_u64 v[216:217], v[166:167], 0, s[12:13]
	s_nop 0
	v_cndmask_b32_e32 v151, v213, v151, vcc
	v_cmp_neq_f32_e32 vcc, -1.0, v204
	s_nop 1
	v_cndmask_b32_e32 v151, v214, v151, vcc
	v_cmp_lt_f32_e64 vcc, |v204|, s39
	s_nop 1
	v_cndmask_b32_e32 v151, v151, v204, vcc
	v_sub_f32_e32 v151, v230, v151
	flat_store_dword v[216:217], v151
